# write-through stores also in the down-projection GEMM epilogue; on top of v57
# speedup vs baseline: 1.0070x; 1.0070x over previous
.LBB0_451:
	s_lshl_b32 s1, s24, 8
	s_ashr_i32 s0, s24, 4
	s_add_i32 s1, s1, s72
	v_mbcnt_lo_u32_b32 v0, -1, 0
	v_mbcnt_hi_u32_b32 v0, -1, v0
	s_mov_b32 s78, 0x2f800000
	v_and_or_b32 v150, v0, 15, s1
	s_mul_hi_i32 s1, s59, s0
	s_mul_i32 s0, s59, s0
	s_lshl_b64 s[0:1], s[0:1], 2
	s_add_u32 s7, s57, s0
	s_addc_u32 s17, s58, s1
	s_lshl_b32 s0, s6, 8
	s_ashr_i32 s1, s0, 31
	s_lshl_b64 s[0:1], s[0:1], 2
	s_add_u32 s0, s7, s0
	s_addc_u32 s1, s17, s1
	v_readlane_b32 s7, v255, 27
	v_bfe_u32 v188, v0, 4, 2
	s_add_u32 s0, s0, s7
	s_addc_u32 s1, s1, 0
	v_lshlrev_b32_e32 v0, 5, v188
	v_lshl_add_u64 v[34:35], s[0:1], 0, v[0:1]
	flat_load_dwordx4 v[46:49], v[34:35]
	flat_load_dwordx4 v[42:45], v[34:35] offset:16
	flat_load_dwordx4 v[38:41], v[34:35] offset:512
	s_nop 0
	flat_load_dwordx4 v[34:37], v[34:35] offset:528
	s_cmp_ge_i32 s6, s43
	s_cselect_b64 s[24:25], -1, 0
	v_lshlrev_b32_e32 v189, 3, v188
	s_and_b64 vcc, exec, s[24:25]
	s_cbranch_vccnz .LBB0_457
	s_cmp_gt_i32 s6, 1
	s_mov_b64 s[24:25], -1
	s_cbranch_scc0 .LBB0_456
	v_readlane_b32 s0, v254, 55
	v_readlane_b32 s1, v254, 56
	s_andn2_b64 vcc, exec, s[0:1]
	s_cbranch_vccnz .LBB0_455
	v_ashrrev_i32_e32 v151, 31, v150
	v_lshl_add_u64 v[152:153], v[150:151], 3, s[12:13]
	global_load_dwordx2 v[146:147], v[152:153], off
	s_waitcnt vmcnt(0) lgkmcnt(0)
	v_mov_b32_e32 v154, v46
	v_mov_b32_e32 v155, v38
	v_xor_b32_e32 v0, v146, v147
	v_ashrrev_i32_e32 v0, 31, v0
	v_ffbh_i32_e32 v148, v147
	v_add_u32_e32 v0, 32, v0
	v_add_u32_e32 v148, -1, v148
	v_min_u32_e32 v0, v148, v0
	v_lshlrev_b64 v[146:147], v0, v[146:147]
	v_min_u32_e32 v146, 1, v146
	v_or_b32_e32 v146, v147, v146
	v_cvt_f32_i32_e32 v146, v146
	v_sub_u32_e32 v0, 32, v0
	v_lshlrev_b64 v[148:149], 8, v[150:151]
	v_lshl_add_u64 v[148:149], s[10:11], 0, v[148:149]
	v_ldexp_f32 v0, v146, v0
	v_mul_f32_e32 v0, 0x35800000, v0
	v_fmamk_f32 v0, v0, 0x3a000000, v180
	v_cmp_gt_f32_e32 vcc, s73, v0
	v_mul_f32_e32 v146, 0x4b800000, v0
	s_nop 0
	v_cndmask_b32_e32 v0, v0, v146, vcc
	v_rsq_f32_e32 v0, v0
	s_nop 0
	v_mul_f32_e32 v146, 0x45800000, v0
	v_cndmask_b32_e32 v146, v0, v146, vcc
	v_lshlrev_b32_e32 v0, 3, v189
	v_lshl_add_u64 v[170:171], v[148:149], 0, v[0:1]
	flat_load_dwordx4 v[158:161], v[170:171]
	flat_load_dwordx4 v[162:165], v[170:171] offset:32
	v_mov_b32_e32 v148, v142
	v_mov_b32_e32 v149, v134
	v_pk_fma_f32 v[148:149], v[148:149], v[146:147], v[154:155] op_sel_hi:[1,0,1]
	flat_load_dwordx4 v[190:193], v[170:171] offset:48
	s_waitcnt vmcnt(0) lgkmcnt(0)
	v_pk_mul_f32 v[156:157], v[158:159], v[148:149]
	v_pk_mul_f32 v[148:149], v[158:159], v[148:149] op_sel:[0,1] op_sel_hi:[1,0]
	v_sub_f32_e32 v184, v156, v157
	v_add_f32_e32 v147, v148, v149
	v_mov_b32_e32 v148, v138
	v_mov_b32_e32 v149, v130
	v_mov_b32_e32 v156, v42
	v_mov_b32_e32 v157, v34
	v_pk_fma_f32 v[148:149], v[148:149], v[146:147], v[156:157] op_sel_hi:[1,0,1]
	s_nop 0
	v_pk_mul_f32 v[158:159], v[162:163], v[148:149]
	v_pk_mul_f32 v[148:149], v[162:163], v[148:149] op_sel:[0,1] op_sel_hi:[1,0]
	v_sub_f32_e32 v185, v158, v159
	v_mov_b32_e32 v162, v143
	v_mov_b32_e32 v163, v135
	v_mov_b32_e32 v158, v47
	v_mov_b32_e32 v159, v39
	v_pk_fma_f32 v[162:163], v[162:163], v[146:147], v[158:159] op_sel_hi:[1,0,1]
	v_add_f32_e32 v148, v148, v149
	v_pk_mul_f32 v[166:167], v[160:161], v[162:163]
	v_pk_mul_f32 v[160:161], v[160:161], v[162:163] op_sel:[0,1] op_sel_hi:[1,0]
	v_mov_b32_e32 v162, v139
	v_add_f32_e32 v149, v160, v161
	v_mov_b32_e32 v163, v131
	v_mov_b32_e32 v160, v43
	v_mov_b32_e32 v161, v35
	v_pk_fma_f32 v[162:163], v[162:163], v[146:147], v[160:161] op_sel_hi:[1,0,1]
	v_sub_f32_e32 v186, v166, v167
	v_pk_mul_f32 v[166:167], v[164:165], v[162:163]
	v_pk_mul_f32 v[162:163], v[164:165], v[162:163] op_sel:[0,1] op_sel_hi:[1,0]
	v_sub_f32_e32 v187, v166, v167
	flat_load_dwordx4 v[166:169], v[170:171] offset:16
	v_add_f32_e32 v172, v162, v163
	v_mov_b32_e32 v164, v144
	v_mov_b32_e32 v165, v136
	v_mov_b32_e32 v162, v48
	v_mov_b32_e32 v163, v40
	v_pk_fma_f32 v[164:165], v[164:165], v[146:147], v[162:163] op_sel_hi:[1,0,1]
	s_waitcnt vmcnt(0) lgkmcnt(0)
	v_pk_mul_f32 v[182:183], v[166:167], v[164:165]
	v_pk_mul_f32 v[164:165], v[166:167], v[164:165] op_sel:[0,1] op_sel_hi:[1,0]
	v_mov_b32_e32 v166, v140
	v_add_f32_e32 v173, v164, v165
	v_mov_b32_e32 v167, v132
	v_mov_b32_e32 v164, v44
	v_mov_b32_e32 v165, v36
	v_pk_fma_f32 v[166:167], v[166:167], v[146:147], v[164:165] op_sel_hi:[1,0,1]
	v_sub_f32_e32 v194, v182, v183
	v_pk_mul_f32 v[170:171], v[166:167], v[190:191]
	v_pk_mul_f32 v[166:167], v[166:167], v[190:191] op_sel:[1,0] op_sel_hi:[0,1]
	v_sub_f32_e32 v195, v170, v171
	v_add_f32_e32 v196, v166, v167
	v_mov_b32_e32 v170, v145
	v_mov_b32_e32 v171, v137
	v_mov_b32_e32 v166, v49
	v_mov_b32_e32 v167, v41
	v_pk_fma_f32 v[170:171], v[170:171], v[146:147], v[166:167] op_sel_hi:[1,0,1]
	v_cvt_pk_bf16_f32 v190, v184, v186
	s_nop 0
	v_pk_mul_f32 v[182:183], v[170:171], v[168:169]
	v_pk_mul_f32 v[168:169], v[170:171], v[168:169] op_sel:[1,0] op_sel_hi:[0,1]
	v_add_f32_e32 v197, v168, v169
	v_mov_b32_e32 v170, v141
	v_mov_b32_e32 v171, v133
	v_mov_b32_e32 v168, v45
	v_mov_b32_e32 v169, v37
	v_pk_fma_f32 v[170:171], v[170:171], v[146:147], v[168:169] op_sel_hi:[1,0,1]
	v_sub_f32_e32 v191, v182, v183
	v_pk_mul_f32 v[182:183], v[170:171], v[192:193]
	v_pk_mul_f32 v[170:171], v[170:171], v[192:193] op_sel:[1,0] op_sel_hi:[0,1]
	v_add_f32_e32 v198, v170, v171
	v_lshlrev_b64 v[170:171], 7, v[150:151]
	v_sub_f32_e32 v146, v182, v183
	v_lshl_add_u64 v[182:183], s[14:15], 0, v[170:171]
	v_lshlrev_b32_e32 v170, 1, v189
	v_mov_b32_e32 v171, v1
	v_lshl_add_u64 v[182:183], v[182:183], 0, v[170:171]
	v_cvt_pk_bf16_f32 v191, v194, v191
	v_cvt_pk_bf16_f32 v192, v185, v187
	v_cvt_pk_bf16_f32 v193, v195, v146
	flat_store_dwordx4 v[182:183], v[190:193] sc1
	v_cvt_pk_bf16_f32 v146, v147, v149
	v_cvt_pk_bf16_f32 v147, v173, v197
	v_cvt_pk_bf16_f32 v148, v148, v172
	v_cvt_pk_bf16_f32 v149, v196, v198
	flat_store_dwordx4 v[182:183], v[146:149] offset:64 sc1
	global_load_dwordx2 v[146:147], v[152:153], off offset:128
	v_or_b32_e32 v172, 16, v150
	v_ashrrev_i32_e32 v173, 31, v172
	v_mov_b32_e32 v182, v126
	v_mov_b32_e32 v183, v118
	s_waitcnt vmcnt(0)
	v_xor_b32_e32 v148, v146, v147
	v_ashrrev_i32_e32 v148, 31, v148
	v_ffbh_i32_e32 v149, v147
	v_add_u32_e32 v148, 32, v148
	v_add_u32_e32 v149, -1, v149
	v_min_u32_e32 v148, v149, v148
	v_lshlrev_b64 v[146:147], v148, v[146:147]
	v_min_u32_e32 v146, 1, v146
	v_or_b32_e32 v146, v147, v146
	v_sub_u32_e32 v147, 32, v148
	v_lshlrev_b64 v[148:149], 8, v[172:173]
	v_lshl_add_u64 v[148:149], s[10:11], 0, v[148:149]
	v_lshl_add_u64 v[148:149], v[148:149], 0, v[0:1]
	flat_load_dwordx4 v[190:193], v[148:149]
	flat_load_dwordx4 v[194:197], v[148:149] offset:32
	v_cvt_f32_i32_e32 v146, v146
	v_lshlrev_b64 v[172:173], 7, v[172:173]
	v_lshl_add_u64 v[172:173], s[14:15], 0, v[172:173]
	v_lshl_add_u64 v[172:173], v[172:173], 0, v[170:171]
	v_ldexp_f32 v146, v146, v147
	v_mul_f32_e32 v146, 0x35800000, v146
	v_fmamk_f32 v146, v146, 0x3a000000, v180
	v_cmp_gt_f32_e32 vcc, s73, v146
	v_mul_f32_e32 v147, 0x4b800000, v146
	flat_load_dwordx4 v[198:201], v[148:149] offset:48
	v_cndmask_b32_e32 v146, v146, v147, vcc
	v_rsq_f32_e32 v146, v146
	s_nop 0
	v_mul_f32_e32 v147, 0x45800000, v146
	v_cndmask_b32_e32 v146, v146, v147, vcc
	v_pk_fma_f32 v[182:183], v[182:183], v[146:147], v[154:155] op_sel_hi:[1,0,1]
	s_waitcnt vmcnt(0) lgkmcnt(0)
	v_pk_mul_f32 v[184:185], v[190:191], v[182:183]
	v_pk_mul_f32 v[182:183], v[190:191], v[182:183] op_sel:[0,1] op_sel_hi:[1,0]
	v_sub_f32_e32 v186, v184, v185
	v_add_f32_e32 v151, v182, v183
	v_mov_b32_e32 v182, v122
	v_mov_b32_e32 v183, v114
	v_pk_fma_f32 v[182:183], v[182:183], v[146:147], v[156:157] op_sel_hi:[1,0,1]
	s_nop 0
	v_pk_mul_f32 v[184:185], v[194:195], v[182:183]
	v_pk_mul_f32 v[182:183], v[194:195], v[182:183] op_sel:[0,1] op_sel_hi:[1,0]
	v_sub_f32_e32 v187, v184, v185
	v_add_f32_e32 v190, v182, v183
	v_mov_b32_e32 v182, v127
	v_mov_b32_e32 v183, v119
	v_pk_fma_f32 v[182:183], v[182:183], v[146:147], v[158:159] op_sel_hi:[1,0,1]
	s_nop 0
	v_pk_mul_f32 v[184:185], v[192:193], v[182:183]
	v_pk_mul_f32 v[182:183], v[192:193], v[182:183] op_sel:[0,1] op_sel_hi:[1,0]
	v_sub_f32_e32 v202, v184, v185
	v_add_f32_e32 v191, v182, v183
	v_mov_b32_e32 v182, v123
	v_mov_b32_e32 v183, v115
	v_pk_fma_f32 v[182:183], v[182:183], v[146:147], v[160:161] op_sel_hi:[1,0,1]
	s_nop 0
	v_pk_mul_f32 v[184:185], v[196:197], v[182:183]
	v_pk_mul_f32 v[182:183], v[196:197], v[182:183] op_sel:[0,1] op_sel_hi:[1,0]
	flat_load_dwordx4 v[194:197], v[148:149] offset:16
	v_add_f32_e32 v192, v182, v183
	v_mov_b32_e32 v182, v128
	v_mov_b32_e32 v183, v120
	v_pk_fma_f32 v[182:183], v[182:183], v[146:147], v[162:163] op_sel_hi:[1,0,1]
	v_mov_b32_e32 v148, v124
	v_mov_b32_e32 v149, v116
	v_sub_f32_e32 v193, v184, v185
	v_pk_fma_f32 v[148:149], v[148:149], v[146:147], v[164:165] op_sel_hi:[1,0,1]
	s_waitcnt vmcnt(0) lgkmcnt(0)
	v_pk_mul_f32 v[184:185], v[194:195], v[182:183]
	v_pk_mul_f32 v[182:183], v[194:195], v[182:183] op_sel:[0,1] op_sel_hi:[1,0]
	v_sub_f32_e32 v184, v184, v185
	v_add_f32_e32 v185, v182, v183
	v_pk_mul_f32 v[182:183], v[148:149], v[198:199]
	v_pk_mul_f32 v[148:149], v[148:149], v[198:199] op_sel:[1,0] op_sel_hi:[0,1]
	v_add_f32_e32 v195, v148, v149
	v_mov_b32_e32 v148, v129
	v_mov_b32_e32 v149, v121
	v_pk_fma_f32 v[148:149], v[148:149], v[146:147], v[166:167] op_sel_hi:[1,0,1]
	v_sub_f32_e32 v194, v182, v183
	v_pk_mul_f32 v[182:183], v[148:149], v[196:197]
	v_pk_mul_f32 v[148:149], v[148:149], v[196:197] op_sel:[1,0] op_sel_hi:[0,1]
	v_sub_f32_e32 v182, v182, v183
	v_add_f32_e32 v183, v148, v149
	v_mov_b32_e32 v148, v125
	v_mov_b32_e32 v149, v117
	v_pk_fma_f32 v[146:147], v[148:149], v[146:147], v[168:169] op_sel_hi:[1,0,1]
	s_nop 0
	v_pk_mul_f32 v[148:149], v[146:147], v[200:201]
	v_pk_mul_f32 v[146:147], v[146:147], v[200:201] op_sel:[1,0] op_sel_hi:[0,1]
	v_sub_f32_e32 v149, v148, v149
	v_add_f32_e32 v196, v146, v147
	v_cvt_pk_bf16_f32 v146, v186, v202
	v_cvt_pk_bf16_f32 v147, v184, v182
	v_cvt_pk_bf16_f32 v148, v187, v193
	v_cvt_pk_bf16_f32 v149, v194, v149
	flat_store_dwordx4 v[172:173], v[146:149] sc1
	v_mov_b32_e32 v182, v110
	s_nop 0
	v_cvt_pk_bf16_f32 v146, v151, v191
	v_cvt_pk_bf16_f32 v147, v185, v183
	v_cvt_pk_bf16_f32 v148, v190, v192
	v_cvt_pk_bf16_f32 v149, v195, v196
	flat_store_dwordx4 v[172:173], v[146:149] offset:64 sc1
	global_load_dwordx2 v[146:147], v[152:153], off offset:256
	v_or_b32_e32 v172, 32, v150
	v_ashrrev_i32_e32 v173, 31, v172
	v_mov_b32_e32 v183, v102
	s_waitcnt vmcnt(0)
	v_xor_b32_e32 v148, v146, v147
	v_ashrrev_i32_e32 v148, 31, v148
	v_ffbh_i32_e32 v149, v147
	v_add_u32_e32 v148, 32, v148
	v_add_u32_e32 v149, -1, v149
	v_min_u32_e32 v148, v149, v148
	v_lshlrev_b64 v[146:147], v148, v[146:147]
	v_min_u32_e32 v146, 1, v146
	v_or_b32_e32 v146, v147, v146
	v_sub_u32_e32 v147, 32, v148
	v_lshlrev_b64 v[148:149], 8, v[172:173]
	v_lshl_add_u64 v[148:149], s[10:11], 0, v[148:149]
	v_lshl_add_u64 v[148:149], v[148:149], 0, v[0:1]
	flat_load_dwordx4 v[190:193], v[148:149]
	flat_load_dwordx4 v[194:197], v[148:149] offset:32
	v_cvt_f32_i32_e32 v146, v146
	flat_load_dwordx4 v[198:201], v[148:149] offset:48
	v_lshlrev_b64 v[172:173], 7, v[172:173]
	v_lshl_add_u64 v[172:173], s[14:15], 0, v[172:173]
	v_ldexp_f32 v146, v146, v147
	v_mul_f32_e32 v146, 0x35800000, v146
	v_fmamk_f32 v146, v146, 0x3a000000, v180
	v_cmp_gt_f32_e32 vcc, s73, v146
	v_mul_f32_e32 v147, 0x4b800000, v146
	v_lshl_add_u64 v[172:173], v[172:173], 0, v[170:171]
	v_cndmask_b32_e32 v146, v146, v147, vcc
	v_rsq_f32_e32 v146, v146
	s_nop 0
	v_mul_f32_e32 v147, 0x45800000, v146
	v_cndmask_b32_e32 v146, v146, v147, vcc
	v_pk_fma_f32 v[182:183], v[182:183], v[146:147], v[154:155] op_sel_hi:[1,0,1]
	s_waitcnt vmcnt(0) lgkmcnt(0)
	v_pk_mul_f32 v[184:185], v[190:191], v[182:183]
	v_pk_mul_f32 v[182:183], v[190:191], v[182:183] op_sel:[0,1] op_sel_hi:[1,0]
	v_sub_f32_e32 v186, v184, v185
	v_add_f32_e32 v151, v182, v183
	v_mov_b32_e32 v182, v106
	v_mov_b32_e32 v183, v98
	v_pk_fma_f32 v[182:183], v[182:183], v[146:147], v[156:157] op_sel_hi:[1,0,1]
	s_nop 0
	v_pk_mul_f32 v[184:185], v[194:195], v[182:183]
	v_pk_mul_f32 v[182:183], v[194:195], v[182:183] op_sel:[0,1] op_sel_hi:[1,0]
	v_sub_f32_e32 v187, v184, v185
	v_add_f32_e32 v190, v182, v183
	v_mov_b32_e32 v182, v111
	v_mov_b32_e32 v183, v103
	v_pk_fma_f32 v[182:183], v[182:183], v[146:147], v[158:159] op_sel_hi:[1,0,1]
	s_nop 0
	v_pk_mul_f32 v[184:185], v[192:193], v[182:183]
	v_pk_mul_f32 v[182:183], v[192:193], v[182:183] op_sel:[0,1] op_sel_hi:[1,0]
	v_sub_f32_e32 v202, v184, v185
	v_add_f32_e32 v191, v182, v183
	v_mov_b32_e32 v182, v107
	v_mov_b32_e32 v183, v99
	v_pk_fma_f32 v[182:183], v[182:183], v[146:147], v[160:161] op_sel_hi:[1,0,1]
	s_nop 0
	v_pk_mul_f32 v[184:185], v[196:197], v[182:183]
	v_pk_mul_f32 v[182:183], v[196:197], v[182:183] op_sel:[0,1] op_sel_hi:[1,0]
	flat_load_dwordx4 v[194:197], v[148:149] offset:16
	v_add_f32_e32 v192, v182, v183
	v_mov_b32_e32 v182, v112
	v_mov_b32_e32 v183, v104
	v_pk_fma_f32 v[182:183], v[182:183], v[146:147], v[162:163] op_sel_hi:[1,0,1]
	v_mov_b32_e32 v148, v108
	v_mov_b32_e32 v149, v100
	v_sub_f32_e32 v193, v184, v185
	v_pk_fma_f32 v[148:149], v[148:149], v[146:147], v[164:165] op_sel_hi:[1,0,1]
	s_waitcnt vmcnt(0) lgkmcnt(0)
	v_pk_mul_f32 v[184:185], v[194:195], v[182:183]
	v_pk_mul_f32 v[182:183], v[194:195], v[182:183] op_sel:[0,1] op_sel_hi:[1,0]
	v_sub_f32_e32 v184, v184, v185
	v_add_f32_e32 v185, v182, v183
	v_pk_mul_f32 v[182:183], v[148:149], v[198:199]
	v_pk_mul_f32 v[148:149], v[148:149], v[198:199] op_sel:[1,0] op_sel_hi:[0,1]
	v_add_f32_e32 v195, v148, v149
	v_mov_b32_e32 v148, v113
	v_mov_b32_e32 v149, v105
	v_pk_fma_f32 v[148:149], v[148:149], v[146:147], v[166:167] op_sel_hi:[1,0,1]
	v_sub_f32_e32 v194, v182, v183
	v_pk_mul_f32 v[182:183], v[148:149], v[196:197]
	v_pk_mul_f32 v[148:149], v[148:149], v[196:197] op_sel:[1,0] op_sel_hi:[0,1]
	v_sub_f32_e32 v182, v182, v183
	v_add_f32_e32 v183, v148, v149
	v_mov_b32_e32 v148, v109
	v_mov_b32_e32 v149, v101
	v_pk_fma_f32 v[146:147], v[148:149], v[146:147], v[168:169] op_sel_hi:[1,0,1]
	s_nop 0
	v_pk_mul_f32 v[148:149], v[146:147], v[200:201]
	v_pk_mul_f32 v[146:147], v[146:147], v[200:201] op_sel:[1,0] op_sel_hi:[0,1]
	v_sub_f32_e32 v149, v148, v149
	v_add_f32_e32 v196, v146, v147
	v_cvt_pk_bf16_f32 v146, v186, v202
	v_cvt_pk_bf16_f32 v147, v184, v182
	v_cvt_pk_bf16_f32 v148, v187, v193
	v_cvt_pk_bf16_f32 v149, v194, v149
	flat_store_dwordx4 v[172:173], v[146:149] sc1
	v_mov_b32_e32 v182, v94
	s_nop 0
	v_cvt_pk_bf16_f32 v146, v151, v191
	v_cvt_pk_bf16_f32 v147, v185, v183
	v_cvt_pk_bf16_f32 v148, v190, v192
	v_cvt_pk_bf16_f32 v149, v195, v196
	flat_store_dwordx4 v[172:173], v[146:149] offset:64 sc1
	global_load_dwordx2 v[146:147], v[152:153], off offset:384
	v_or_b32_e32 v172, 48, v150
	v_ashrrev_i32_e32 v173, 31, v172
	v_mov_b32_e32 v183, v86
	s_waitcnt vmcnt(0)
	v_xor_b32_e32 v148, v146, v147
	v_ashrrev_i32_e32 v148, 31, v148
	v_ffbh_i32_e32 v149, v147
	v_add_u32_e32 v148, 32, v148
	v_add_u32_e32 v149, -1, v149
	v_min_u32_e32 v148, v149, v148
	v_lshlrev_b64 v[146:147], v148, v[146:147]
	v_min_u32_e32 v146, 1, v146
	v_or_b32_e32 v146, v147, v146
	v_sub_u32_e32 v147, 32, v148
	v_lshlrev_b64 v[148:149], 8, v[172:173]
	v_lshl_add_u64 v[148:149], s[10:11], 0, v[148:149]
	v_lshl_add_u64 v[148:149], v[148:149], 0, v[0:1]
	flat_load_dwordx4 v[190:193], v[148:149]
	flat_load_dwordx4 v[194:197], v[148:149] offset:32
	v_cvt_f32_i32_e32 v146, v146
	flat_load_dwordx4 v[198:201], v[148:149] offset:48
	v_lshlrev_b64 v[172:173], 7, v[172:173]
	v_lshl_add_u64 v[172:173], s[14:15], 0, v[172:173]
	v_ldexp_f32 v146, v146, v147
	v_mul_f32_e32 v146, 0x35800000, v146
	v_fmamk_f32 v146, v146, 0x3a000000, v180
	v_cmp_gt_f32_e32 vcc, s73, v146
	v_mul_f32_e32 v147, 0x4b800000, v146
	v_lshl_add_u64 v[172:173], v[172:173], 0, v[170:171]
	v_cndmask_b32_e32 v146, v146, v147, vcc
	v_rsq_f32_e32 v146, v146
	s_nop 0
	v_mul_f32_e32 v147, 0x45800000, v146
	v_cndmask_b32_e32 v146, v146, v147, vcc
	v_pk_fma_f32 v[182:183], v[182:183], v[146:147], v[154:155] op_sel_hi:[1,0,1]
	s_waitcnt vmcnt(0) lgkmcnt(0)
	v_pk_mul_f32 v[184:185], v[190:191], v[182:183]
	v_pk_mul_f32 v[182:183], v[190:191], v[182:183] op_sel:[0,1] op_sel_hi:[1,0]
	v_sub_f32_e32 v186, v184, v185
	v_add_f32_e32 v151, v182, v183
	v_mov_b32_e32 v182, v90
	v_mov_b32_e32 v183, v82
	v_pk_fma_f32 v[182:183], v[182:183], v[146:147], v[156:157] op_sel_hi:[1,0,1]
	s_nop 0
	v_pk_mul_f32 v[184:185], v[194:195], v[182:183]
	v_pk_mul_f32 v[182:183], v[194:195], v[182:183] op_sel:[0,1] op_sel_hi:[1,0]
	v_sub_f32_e32 v187, v184, v185
	v_add_f32_e32 v190, v182, v183
	v_mov_b32_e32 v182, v95
	v_mov_b32_e32 v183, v87
	v_pk_fma_f32 v[182:183], v[182:183], v[146:147], v[158:159] op_sel_hi:[1,0,1]
	s_nop 0
	v_pk_mul_f32 v[184:185], v[192:193], v[182:183]
	v_pk_mul_f32 v[182:183], v[192:193], v[182:183] op_sel:[0,1] op_sel_hi:[1,0]
	v_sub_f32_e32 v202, v184, v185
	v_add_f32_e32 v191, v182, v183
	v_mov_b32_e32 v182, v91
	v_mov_b32_e32 v183, v83
	v_pk_fma_f32 v[182:183], v[182:183], v[146:147], v[160:161] op_sel_hi:[1,0,1]
	s_nop 0
	v_pk_mul_f32 v[184:185], v[196:197], v[182:183]
	v_pk_mul_f32 v[182:183], v[196:197], v[182:183] op_sel:[0,1] op_sel_hi:[1,0]
	flat_load_dwordx4 v[194:197], v[148:149] offset:16
	v_add_f32_e32 v192, v182, v183
	v_mov_b32_e32 v182, v96
	v_mov_b32_e32 v183, v88
	v_pk_fma_f32 v[182:183], v[182:183], v[146:147], v[162:163] op_sel_hi:[1,0,1]
	v_mov_b32_e32 v148, v92
	v_mov_b32_e32 v149, v84
	v_sub_f32_e32 v193, v184, v185
	v_pk_fma_f32 v[148:149], v[148:149], v[146:147], v[164:165] op_sel_hi:[1,0,1]
	s_waitcnt vmcnt(0) lgkmcnt(0)
	v_pk_mul_f32 v[184:185], v[194:195], v[182:183]
	v_pk_mul_f32 v[182:183], v[194:195], v[182:183] op_sel:[0,1] op_sel_hi:[1,0]
	v_sub_f32_e32 v184, v184, v185
	v_add_f32_e32 v185, v182, v183
	v_pk_mul_f32 v[182:183], v[148:149], v[198:199]
	v_pk_mul_f32 v[148:149], v[148:149], v[198:199] op_sel:[1,0] op_sel_hi:[0,1]
	v_add_f32_e32 v195, v148, v149
	v_mov_b32_e32 v148, v97
	v_mov_b32_e32 v149, v89
	v_pk_fma_f32 v[148:149], v[148:149], v[146:147], v[166:167] op_sel_hi:[1,0,1]
	v_sub_f32_e32 v194, v182, v183
	v_pk_mul_f32 v[182:183], v[148:149], v[196:197]
	v_pk_mul_f32 v[148:149], v[148:149], v[196:197] op_sel:[1,0] op_sel_hi:[0,1]
	v_sub_f32_e32 v182, v182, v183
	v_add_f32_e32 v183, v148, v149
	v_mov_b32_e32 v148, v93
	v_mov_b32_e32 v149, v85
	v_pk_fma_f32 v[146:147], v[148:149], v[146:147], v[168:169] op_sel_hi:[1,0,1]
	s_nop 0
	v_pk_mul_f32 v[148:149], v[146:147], v[200:201]
	v_pk_mul_f32 v[146:147], v[146:147], v[200:201] op_sel:[1,0] op_sel_hi:[0,1]
	v_sub_f32_e32 v149, v148, v149
	v_add_f32_e32 v196, v146, v147
	v_cvt_pk_bf16_f32 v146, v186, v202
	v_cvt_pk_bf16_f32 v147, v184, v182
	v_cvt_pk_bf16_f32 v148, v187, v193
	v_cvt_pk_bf16_f32 v149, v194, v149
	flat_store_dwordx4 v[172:173], v[146:149] sc1
	v_mov_b32_e32 v182, v78
	s_nop 0
	v_cvt_pk_bf16_f32 v146, v151, v191
	v_cvt_pk_bf16_f32 v147, v185, v183
	v_cvt_pk_bf16_f32 v148, v190, v192
	v_cvt_pk_bf16_f32 v149, v195, v196
	flat_store_dwordx4 v[172:173], v[146:149] offset:64 sc1
	global_load_dwordx2 v[146:147], v[152:153], off offset:1024
	v_add_u32_e32 v172, 0x80, v150
	v_ashrrev_i32_e32 v173, 31, v172
	v_mov_b32_e32 v183, v70
	s_waitcnt vmcnt(0)
	v_xor_b32_e32 v148, v146, v147
	v_ashrrev_i32_e32 v148, 31, v148
	v_ffbh_i32_e32 v149, v147
	v_add_u32_e32 v148, 32, v148
	v_add_u32_e32 v149, -1, v149
	v_min_u32_e32 v148, v149, v148
	v_lshlrev_b64 v[146:147], v148, v[146:147]
	v_min_u32_e32 v146, 1, v146
	v_or_b32_e32 v146, v147, v146
	v_sub_u32_e32 v147, 32, v148
	v_lshlrev_b64 v[148:149], 8, v[172:173]
	v_lshl_add_u64 v[148:149], s[10:11], 0, v[148:149]
	v_lshl_add_u64 v[148:149], v[148:149], 0, v[0:1]
	flat_load_dwordx4 v[190:193], v[148:149]
	flat_load_dwordx4 v[194:197], v[148:149] offset:32
	v_cvt_f32_i32_e32 v146, v146
	flat_load_dwordx4 v[198:201], v[148:149] offset:48
	v_lshlrev_b64 v[172:173], 7, v[172:173]
	v_lshl_add_u64 v[172:173], s[14:15], 0, v[172:173]
	v_ldexp_f32 v146, v146, v147
	v_mul_f32_e32 v146, 0x35800000, v146
	v_fmamk_f32 v146, v146, 0x3a000000, v180
	v_cmp_gt_f32_e32 vcc, s73, v146
	v_mul_f32_e32 v147, 0x4b800000, v146
	v_lshl_add_u64 v[172:173], v[172:173], 0, v[170:171]
	v_cndmask_b32_e32 v146, v146, v147, vcc
	v_rsq_f32_e32 v146, v146
	s_nop 0
	v_mul_f32_e32 v147, 0x45800000, v146
	v_cndmask_b32_e32 v146, v146, v147, vcc
	v_pk_fma_f32 v[182:183], v[182:183], v[146:147], v[154:155] op_sel_hi:[1,0,1]
	s_waitcnt vmcnt(0) lgkmcnt(0)
	v_pk_mul_f32 v[184:185], v[190:191], v[182:183]
	v_pk_mul_f32 v[182:183], v[190:191], v[182:183] op_sel:[0,1] op_sel_hi:[1,0]
	v_sub_f32_e32 v186, v184, v185
	v_add_f32_e32 v151, v182, v183
	v_mov_b32_e32 v182, v74
	v_mov_b32_e32 v183, v66
	v_pk_fma_f32 v[182:183], v[182:183], v[146:147], v[156:157] op_sel_hi:[1,0,1]
	s_nop 0
	v_pk_mul_f32 v[184:185], v[194:195], v[182:183]
	v_pk_mul_f32 v[182:183], v[194:195], v[182:183] op_sel:[0,1] op_sel_hi:[1,0]
	v_sub_f32_e32 v187, v184, v185
	v_add_f32_e32 v190, v182, v183
	v_mov_b32_e32 v182, v79
	v_mov_b32_e32 v183, v71
	v_pk_fma_f32 v[182:183], v[182:183], v[146:147], v[158:159] op_sel_hi:[1,0,1]
	s_nop 0
	v_pk_mul_f32 v[184:185], v[192:193], v[182:183]
	v_pk_mul_f32 v[182:183], v[192:193], v[182:183] op_sel:[0,1] op_sel_hi:[1,0]
	v_sub_f32_e32 v202, v184, v185
	v_add_f32_e32 v191, v182, v183
	v_mov_b32_e32 v182, v75
	v_mov_b32_e32 v183, v67
	v_pk_fma_f32 v[182:183], v[182:183], v[146:147], v[160:161] op_sel_hi:[1,0,1]
	s_nop 0
	v_pk_mul_f32 v[184:185], v[196:197], v[182:183]
	v_pk_mul_f32 v[182:183], v[196:197], v[182:183] op_sel:[0,1] op_sel_hi:[1,0]
	flat_load_dwordx4 v[194:197], v[148:149] offset:16
	v_add_f32_e32 v192, v182, v183
	v_mov_b32_e32 v182, v80
	v_mov_b32_e32 v183, v72
	v_pk_fma_f32 v[182:183], v[182:183], v[146:147], v[162:163] op_sel_hi:[1,0,1]
	v_mov_b32_e32 v148, v76
	v_mov_b32_e32 v149, v68
	v_sub_f32_e32 v193, v184, v185
	v_pk_fma_f32 v[148:149], v[148:149], v[146:147], v[164:165] op_sel_hi:[1,0,1]
	s_waitcnt vmcnt(0) lgkmcnt(0)
	v_pk_mul_f32 v[184:185], v[194:195], v[182:183]
	v_pk_mul_f32 v[182:183], v[194:195], v[182:183] op_sel:[0,1] op_sel_hi:[1,0]
	v_sub_f32_e32 v184, v184, v185
	v_add_f32_e32 v185, v182, v183
	v_pk_mul_f32 v[182:183], v[148:149], v[198:199]
	v_pk_mul_f32 v[148:149], v[148:149], v[198:199] op_sel:[1,0] op_sel_hi:[0,1]
	v_add_f32_e32 v195, v148, v149
	v_mov_b32_e32 v148, v81
	v_mov_b32_e32 v149, v73
	v_pk_fma_f32 v[148:149], v[148:149], v[146:147], v[166:167] op_sel_hi:[1,0,1]
	v_sub_f32_e32 v194, v182, v183
	v_pk_mul_f32 v[182:183], v[148:149], v[196:197]
	v_pk_mul_f32 v[148:149], v[148:149], v[196:197] op_sel:[1,0] op_sel_hi:[0,1]
	v_sub_f32_e32 v182, v182, v183
	v_add_f32_e32 v183, v148, v149
	v_mov_b32_e32 v148, v77
	v_mov_b32_e32 v149, v69
	v_pk_fma_f32 v[146:147], v[148:149], v[146:147], v[168:169] op_sel_hi:[1,0,1]
	s_nop 0
	v_pk_mul_f32 v[148:149], v[146:147], v[200:201]
	v_pk_mul_f32 v[146:147], v[146:147], v[200:201] op_sel:[1,0] op_sel_hi:[0,1]
	v_sub_f32_e32 v149, v148, v149
	v_add_f32_e32 v196, v146, v147
	v_cvt_pk_bf16_f32 v146, v186, v202
	v_cvt_pk_bf16_f32 v147, v184, v182
	v_cvt_pk_bf16_f32 v148, v187, v193
	v_cvt_pk_bf16_f32 v149, v194, v149
	flat_store_dwordx4 v[172:173], v[146:149] sc1
	v_mov_b32_e32 v182, v62
	s_nop 0
	v_cvt_pk_bf16_f32 v146, v151, v191
	v_cvt_pk_bf16_f32 v147, v185, v183
	v_cvt_pk_bf16_f32 v148, v190, v192
	v_cvt_pk_bf16_f32 v149, v195, v196
	flat_store_dwordx4 v[172:173], v[146:149] offset:64 sc1
	global_load_dwordx2 v[146:147], v[152:153], off offset:1152
	v_add_u32_e32 v172, 0x90, v150
	v_ashrrev_i32_e32 v173, 31, v172
	v_mov_b32_e32 v183, v54
	s_waitcnt vmcnt(0)
	v_xor_b32_e32 v148, v146, v147
	v_ashrrev_i32_e32 v148, 31, v148
	v_ffbh_i32_e32 v149, v147
	v_add_u32_e32 v148, 32, v148
	v_add_u32_e32 v149, -1, v149
	v_min_u32_e32 v148, v149, v148
	v_lshlrev_b64 v[146:147], v148, v[146:147]
	v_min_u32_e32 v146, 1, v146
	v_or_b32_e32 v146, v147, v146
	v_sub_u32_e32 v147, 32, v148
	v_lshlrev_b64 v[148:149], 8, v[172:173]
	v_lshl_add_u64 v[148:149], s[10:11], 0, v[148:149]
	v_lshl_add_u64 v[148:149], v[148:149], 0, v[0:1]
	flat_load_dwordx4 v[190:193], v[148:149]
	flat_load_dwordx4 v[194:197], v[148:149] offset:32
	v_cvt_f32_i32_e32 v146, v146
	flat_load_dwordx4 v[198:201], v[148:149] offset:48
	v_lshlrev_b64 v[172:173], 7, v[172:173]
	v_lshl_add_u64 v[172:173], s[14:15], 0, v[172:173]
	v_ldexp_f32 v146, v146, v147
	v_mul_f32_e32 v146, 0x35800000, v146
	v_fmamk_f32 v146, v146, 0x3a000000, v180
	v_cmp_gt_f32_e32 vcc, s73, v146
	v_mul_f32_e32 v147, 0x4b800000, v146
	v_lshl_add_u64 v[172:173], v[172:173], 0, v[170:171]
	v_cndmask_b32_e32 v146, v146, v147, vcc
	v_rsq_f32_e32 v146, v146
	s_nop 0
	v_mul_f32_e32 v147, 0x45800000, v146
	v_cndmask_b32_e32 v146, v146, v147, vcc
	v_pk_fma_f32 v[182:183], v[182:183], v[146:147], v[154:155] op_sel_hi:[1,0,1]
	s_waitcnt vmcnt(0) lgkmcnt(0)
	v_pk_mul_f32 v[184:185], v[190:191], v[182:183]
	v_pk_mul_f32 v[182:183], v[190:191], v[182:183] op_sel:[0,1] op_sel_hi:[1,0]
	v_sub_f32_e32 v186, v184, v185
	v_add_f32_e32 v151, v182, v183
	v_mov_b32_e32 v182, v58
	v_mov_b32_e32 v183, v50
	v_pk_fma_f32 v[182:183], v[182:183], v[146:147], v[156:157] op_sel_hi:[1,0,1]
	s_nop 0
	v_pk_mul_f32 v[184:185], v[194:195], v[182:183]
	v_pk_mul_f32 v[182:183], v[194:195], v[182:183] op_sel:[0,1] op_sel_hi:[1,0]
	v_sub_f32_e32 v187, v184, v185
	v_add_f32_e32 v190, v182, v183
	v_mov_b32_e32 v182, v63
	v_mov_b32_e32 v183, v55
	v_pk_fma_f32 v[182:183], v[182:183], v[146:147], v[158:159] op_sel_hi:[1,0,1]
	s_nop 0
	v_pk_mul_f32 v[184:185], v[192:193], v[182:183]
	v_pk_mul_f32 v[182:183], v[192:193], v[182:183] op_sel:[0,1] op_sel_hi:[1,0]
	v_sub_f32_e32 v202, v184, v185
	v_add_f32_e32 v191, v182, v183
	v_mov_b32_e32 v182, v59
	v_mov_b32_e32 v183, v51
	v_pk_fma_f32 v[182:183], v[182:183], v[146:147], v[160:161] op_sel_hi:[1,0,1]
	s_nop 0
	v_pk_mul_f32 v[184:185], v[196:197], v[182:183]
	v_pk_mul_f32 v[182:183], v[196:197], v[182:183] op_sel:[0,1] op_sel_hi:[1,0]
	flat_load_dwordx4 v[194:197], v[148:149] offset:16
	v_add_f32_e32 v192, v182, v183
	v_mov_b32_e32 v182, v64
	v_mov_b32_e32 v183, v56
	v_pk_fma_f32 v[182:183], v[182:183], v[146:147], v[162:163] op_sel_hi:[1,0,1]
	v_mov_b32_e32 v148, v60
	v_mov_b32_e32 v149, v52
	v_sub_f32_e32 v193, v184, v185
	v_pk_fma_f32 v[148:149], v[148:149], v[146:147], v[164:165] op_sel_hi:[1,0,1]
	s_waitcnt vmcnt(0) lgkmcnt(0)
	v_pk_mul_f32 v[184:185], v[194:195], v[182:183]
	v_pk_mul_f32 v[182:183], v[194:195], v[182:183] op_sel:[0,1] op_sel_hi:[1,0]
	v_sub_f32_e32 v184, v184, v185
	v_add_f32_e32 v185, v182, v183
	v_pk_mul_f32 v[182:183], v[148:149], v[198:199]
	v_pk_mul_f32 v[148:149], v[148:149], v[198:199] op_sel:[1,0] op_sel_hi:[0,1]
	v_add_f32_e32 v195, v148, v149
	v_mov_b32_e32 v148, v65
	v_mov_b32_e32 v149, v57
	v_pk_fma_f32 v[148:149], v[148:149], v[146:147], v[166:167] op_sel_hi:[1,0,1]
	v_sub_f32_e32 v194, v182, v183
	v_pk_mul_f32 v[182:183], v[148:149], v[196:197]
	v_pk_mul_f32 v[148:149], v[148:149], v[196:197] op_sel:[1,0] op_sel_hi:[0,1]
	v_sub_f32_e32 v182, v182, v183
	v_add_f32_e32 v183, v148, v149
	v_mov_b32_e32 v148, v61
	v_mov_b32_e32 v149, v53
	v_pk_fma_f32 v[146:147], v[148:149], v[146:147], v[168:169] op_sel_hi:[1,0,1]
	s_nop 0
	v_pk_mul_f32 v[148:149], v[146:147], v[200:201]
	v_pk_mul_f32 v[146:147], v[146:147], v[200:201] op_sel:[1,0] op_sel_hi:[0,1]
	v_sub_f32_e32 v149, v148, v149
	v_add_f32_e32 v196, v146, v147
	v_cvt_pk_bf16_f32 v146, v186, v202
	v_cvt_pk_bf16_f32 v147, v184, v182
	v_cvt_pk_bf16_f32 v148, v187, v193
	v_cvt_pk_bf16_f32 v149, v194, v149
	flat_store_dwordx4 v[172:173], v[146:149] sc1
	v_mov_b32_e32 v182, v30
	s_nop 0
	v_cvt_pk_bf16_f32 v146, v151, v191
	v_cvt_pk_bf16_f32 v147, v185, v183
	v_cvt_pk_bf16_f32 v148, v190, v192
	v_cvt_pk_bf16_f32 v149, v195, v196
	flat_store_dwordx4 v[172:173], v[146:149] offset:64 sc1
	global_load_dwordx2 v[146:147], v[152:153], off offset:1280
	v_add_u32_e32 v172, 0xa0, v150
	v_ashrrev_i32_e32 v173, 31, v172
	v_mov_b32_e32 v183, v22
	s_waitcnt vmcnt(0)
	v_xor_b32_e32 v148, v146, v147
	v_ashrrev_i32_e32 v148, 31, v148
	v_ffbh_i32_e32 v149, v147
	v_add_u32_e32 v148, 32, v148
	v_add_u32_e32 v149, -1, v149
	v_min_u32_e32 v148, v149, v148
	v_lshlrev_b64 v[146:147], v148, v[146:147]
	v_min_u32_e32 v146, 1, v146
	v_or_b32_e32 v146, v147, v146
	v_sub_u32_e32 v147, 32, v148
	v_lshlrev_b64 v[148:149], 8, v[172:173]
	v_lshl_add_u64 v[148:149], s[10:11], 0, v[148:149]
	v_lshl_add_u64 v[148:149], v[148:149], 0, v[0:1]
	flat_load_dwordx4 v[190:193], v[148:149]
	flat_load_dwordx4 v[194:197], v[148:149] offset:32
	v_cvt_f32_i32_e32 v146, v146
	flat_load_dwordx4 v[198:201], v[148:149] offset:48
	v_lshlrev_b64 v[172:173], 7, v[172:173]
	v_lshl_add_u64 v[172:173], s[14:15], 0, v[172:173]
	v_ldexp_f32 v146, v146, v147
	v_mul_f32_e32 v146, 0x35800000, v146
	v_fmamk_f32 v146, v146, 0x3a000000, v180
	v_cmp_gt_f32_e32 vcc, s73, v146
	v_mul_f32_e32 v147, 0x4b800000, v146
	v_lshl_add_u64 v[172:173], v[172:173], 0, v[170:171]
	v_cndmask_b32_e32 v146, v146, v147, vcc
	v_rsq_f32_e32 v146, v146
	s_nop 0
	v_mul_f32_e32 v147, 0x45800000, v146
	v_cndmask_b32_e32 v146, v146, v147, vcc
	v_pk_fma_f32 v[182:183], v[182:183], v[146:147], v[154:155] op_sel_hi:[1,0,1]
	s_waitcnt vmcnt(0) lgkmcnt(0)
	v_pk_mul_f32 v[184:185], v[190:191], v[182:183]
	v_pk_mul_f32 v[182:183], v[190:191], v[182:183] op_sel:[0,1] op_sel_hi:[1,0]
	v_sub_f32_e32 v186, v184, v185
	v_add_f32_e32 v151, v182, v183
	v_mov_b32_e32 v182, v26
	v_mov_b32_e32 v183, v18
	v_pk_fma_f32 v[182:183], v[182:183], v[146:147], v[156:157] op_sel_hi:[1,0,1]
	s_nop 0
	v_pk_mul_f32 v[184:185], v[194:195], v[182:183]
	v_pk_mul_f32 v[182:183], v[194:195], v[182:183] op_sel:[0,1] op_sel_hi:[1,0]
	v_sub_f32_e32 v187, v184, v185
	v_add_f32_e32 v190, v182, v183
	v_mov_b32_e32 v182, v31
	v_mov_b32_e32 v183, v23
	v_pk_fma_f32 v[182:183], v[182:183], v[146:147], v[158:159] op_sel_hi:[1,0,1]
	s_nop 0
	v_pk_mul_f32 v[184:185], v[192:193], v[182:183]
	v_pk_mul_f32 v[182:183], v[192:193], v[182:183] op_sel:[0,1] op_sel_hi:[1,0]
	v_sub_f32_e32 v202, v184, v185
	v_add_f32_e32 v191, v182, v183
	v_mov_b32_e32 v182, v27
	v_mov_b32_e32 v183, v19
	v_pk_fma_f32 v[182:183], v[182:183], v[146:147], v[160:161] op_sel_hi:[1,0,1]
	s_nop 0
	v_pk_mul_f32 v[184:185], v[196:197], v[182:183]
	v_pk_mul_f32 v[182:183], v[196:197], v[182:183] op_sel:[0,1] op_sel_hi:[1,0]
	flat_load_dwordx4 v[194:197], v[148:149] offset:16
	v_add_f32_e32 v192, v182, v183
	v_mov_b32_e32 v182, v32
	v_mov_b32_e32 v183, v24
	v_pk_fma_f32 v[182:183], v[182:183], v[146:147], v[162:163] op_sel_hi:[1,0,1]
	v_mov_b32_e32 v148, v28
	v_mov_b32_e32 v149, v20
	v_sub_f32_e32 v193, v184, v185
	v_pk_fma_f32 v[148:149], v[148:149], v[146:147], v[164:165] op_sel_hi:[1,0,1]
	s_waitcnt vmcnt(0) lgkmcnt(0)
	v_pk_mul_f32 v[184:185], v[194:195], v[182:183]
	v_pk_mul_f32 v[182:183], v[194:195], v[182:183] op_sel:[0,1] op_sel_hi:[1,0]
	v_sub_f32_e32 v184, v184, v185
	v_add_f32_e32 v185, v182, v183
	v_pk_mul_f32 v[182:183], v[148:149], v[198:199]
	v_pk_mul_f32 v[148:149], v[148:149], v[198:199] op_sel:[1,0] op_sel_hi:[0,1]
	v_add_f32_e32 v195, v148, v149
	v_mov_b32_e32 v148, v33
	v_mov_b32_e32 v149, v25
	v_pk_fma_f32 v[148:149], v[148:149], v[146:147], v[166:167] op_sel_hi:[1,0,1]
	v_sub_f32_e32 v194, v182, v183
	v_pk_mul_f32 v[182:183], v[148:149], v[196:197]
	v_pk_mul_f32 v[148:149], v[148:149], v[196:197] op_sel:[1,0] op_sel_hi:[0,1]
	v_sub_f32_e32 v182, v182, v183
	v_add_f32_e32 v183, v148, v149
	v_mov_b32_e32 v148, v29
	v_mov_b32_e32 v149, v21
	v_pk_fma_f32 v[146:147], v[148:149], v[146:147], v[168:169] op_sel_hi:[1,0,1]
	s_nop 0
	v_pk_mul_f32 v[148:149], v[146:147], v[200:201]
	v_pk_mul_f32 v[146:147], v[146:147], v[200:201] op_sel:[1,0] op_sel_hi:[0,1]
	v_sub_f32_e32 v149, v148, v149
	v_add_f32_e32 v196, v146, v147
	v_cvt_pk_bf16_f32 v146, v186, v202
	v_cvt_pk_bf16_f32 v147, v184, v182
	v_cvt_pk_bf16_f32 v148, v187, v193
	v_cvt_pk_bf16_f32 v149, v194, v149
	flat_store_dwordx4 v[172:173], v[146:149] sc1
	v_mov_b32_e32 v182, v10
	s_nop 0
	v_cvt_pk_bf16_f32 v146, v151, v191
	v_cvt_pk_bf16_f32 v147, v185, v183
	v_cvt_pk_bf16_f32 v148, v190, v192
	v_cvt_pk_bf16_f32 v149, v195, v196
	flat_store_dwordx4 v[172:173], v[146:149] offset:64 sc1
	global_load_dwordx2 v[146:147], v[152:153], off offset:1408
	v_add_u32_e32 v172, 0xb0, v150
	v_ashrrev_i32_e32 v173, 31, v172
	v_mov_b32_e32 v152, v14
	v_mov_b32_e32 v153, v6
	v_mov_b32_e32 v183, v2
	s_waitcnt vmcnt(0)
	v_xor_b32_e32 v148, v146, v147
	v_ashrrev_i32_e32 v148, 31, v148
	v_ffbh_i32_e32 v149, v147
	v_add_u32_e32 v148, 32, v148
	v_add_u32_e32 v149, -1, v149
	v_min_u32_e32 v148, v149, v148
	v_lshlrev_b64 v[146:147], v148, v[146:147]
	v_min_u32_e32 v146, 1, v146
	v_or_b32_e32 v146, v147, v146
	v_sub_u32_e32 v147, 32, v148
	v_lshlrev_b64 v[148:149], 8, v[172:173]
	v_lshl_add_u64 v[148:149], s[10:11], 0, v[148:149]
	v_lshl_add_u64 v[148:149], v[148:149], 0, v[0:1]
	flat_load_dwordx4 v[190:193], v[148:149]
	v_cvt_f32_i32_e32 v146, v146
	v_ldexp_f32 v146, v146, v147
	v_mul_f32_e32 v146, 0x35800000, v146
	v_fmamk_f32 v146, v146, 0x3a000000, v180
	v_cmp_gt_f32_e32 vcc, s73, v146
	v_mul_f32_e32 v147, 0x4b800000, v146
	s_nop 0
	v_cndmask_b32_e32 v146, v146, v147, vcc
	v_rsq_f32_e32 v146, v146
	s_nop 0
	v_mul_f32_e32 v147, 0x45800000, v146
	v_cndmask_b32_e32 v146, v146, v147, vcc
	v_pk_fma_f32 v[152:153], v[152:153], v[146:147], v[154:155] op_sel_hi:[1,0,1]
	v_pk_fma_f32 v[156:157], v[182:183], v[146:147], v[156:157] op_sel_hi:[1,0,1]
	s_waitcnt vmcnt(0) lgkmcnt(0)
	v_pk_mul_f32 v[154:155], v[190:191], v[152:153]
	v_pk_mul_f32 v[152:153], v[190:191], v[152:153] op_sel:[0,1] op_sel_hi:[1,0]
	v_sub_f32_e32 v184, v154, v155
	v_add_f32_e32 v0, v152, v153
	flat_load_dwordx4 v[152:155], v[148:149] offset:32
	s_waitcnt vmcnt(0) lgkmcnt(0)
	v_pk_mul_f32 v[182:183], v[152:153], v[156:157]
	v_pk_mul_f32 v[152:153], v[152:153], v[156:157] op_sel:[0,1] op_sel_hi:[1,0]
	v_sub_f32_e32 v182, v182, v183
	v_add_f32_e32 v151, v152, v153
	v_mov_b32_e32 v152, v15
	v_mov_b32_e32 v153, v7
	v_pk_fma_f32 v[152:153], v[152:153], v[146:147], v[158:159] op_sel_hi:[1,0,1]
	s_nop 0
	v_pk_mul_f32 v[156:157], v[192:193], v[152:153]
	v_pk_mul_f32 v[152:153], v[192:193], v[152:153] op_sel:[0,1] op_sel_hi:[1,0]
	v_sub_f32_e32 v183, v156, v157
	v_mov_b32_e32 v156, v11
	v_mov_b32_e32 v157, v3
	v_pk_fma_f32 v[156:157], v[156:157], v[146:147], v[160:161] op_sel_hi:[1,0,1]
	v_add_f32_e32 v152, v152, v153
	v_pk_mul_f32 v[158:159], v[154:155], v[156:157]
	v_pk_mul_f32 v[154:155], v[154:155], v[156:157] op_sel:[0,1] op_sel_hi:[1,0]
	v_sub_f32_e32 v185, v158, v159
	v_add_f32_e32 v153, v154, v155
	flat_load_dwordx4 v[154:157], v[148:149] offset:16
	v_mov_b32_e32 v158, v16
	v_mov_b32_e32 v159, v8
	v_pk_fma_f32 v[158:159], v[158:159], v[146:147], v[162:163] op_sel_hi:[1,0,1]
	s_waitcnt vmcnt(0) lgkmcnt(0)
	v_pk_mul_f32 v[160:161], v[154:155], v[158:159]
	s_nop 0
	v_sub_f32_e32 v162, v160, v161
	v_pk_mul_f32 v[154:155], v[154:155], v[158:159] op_sel:[0,1] op_sel_hi:[1,0]
	flat_load_dwordx4 v[158:161], v[148:149] offset:48
	v_mov_b32_e32 v148, v12
	v_mov_b32_e32 v149, v4
	v_pk_fma_f32 v[148:149], v[148:149], v[146:147], v[164:165] op_sel_hi:[1,0,1]
	v_add_f32_e32 v163, v154, v155
	s_waitcnt vmcnt(0) lgkmcnt(0)
	v_pk_mul_f32 v[154:155], v[148:149], v[158:159]
	v_pk_mul_f32 v[148:149], v[148:149], v[158:159] op_sel:[1,0] op_sel_hi:[0,1]
	v_add_f32_e32 v158, v148, v149
	v_mov_b32_e32 v148, v17
	v_mov_b32_e32 v149, v9
	v_pk_fma_f32 v[148:149], v[148:149], v[146:147], v[166:167] op_sel_hi:[1,0,1]
	v_sub_f32_e32 v164, v154, v155
	v_pk_mul_f32 v[154:155], v[148:149], v[156:157]
	v_pk_mul_f32 v[148:149], v[148:149], v[156:157] op_sel:[1,0] op_sel_hi:[0,1]
	v_add_f32_e32 v156, v148, v149
	v_mov_b32_e32 v148, v13
	v_mov_b32_e32 v149, v5
	v_pk_fma_f32 v[146:147], v[148:149], v[146:147], v[168:169] op_sel_hi:[1,0,1]
	v_sub_f32_e32 v154, v154, v155
	v_pk_mul_f32 v[148:149], v[146:147], v[160:161]
	v_pk_mul_f32 v[146:147], v[146:147], v[160:161] op_sel:[1,0] op_sel_hi:[0,1]
	v_add_f32_e32 v157, v146, v147
	v_cvt_pk_bf16_f32 v146, v184, v183
	v_cvt_pk_bf16_f32 v147, v162, v154
	v_lshlrev_b64 v[154:155], 7, v[172:173]
	v_sub_f32_e32 v149, v148, v149
	v_lshl_add_u64 v[154:155], s[14:15], 0, v[154:155]
	v_cvt_pk_bf16_f32 v148, v182, v185
	v_cvt_pk_bf16_f32 v149, v164, v149
	v_lshl_add_u64 v[154:155], v[154:155], 0, v[170:171]
	flat_store_dwordx4 v[154:155], v[146:149] sc1
	s_nop 1
	v_cvt_pk_bf16_f32 v146, v0, v152
	v_cvt_pk_bf16_f32 v147, v163, v156
	v_cvt_pk_bf16_f32 v148, v151, v153
	v_cvt_pk_bf16_f32 v149, v158, v157
	flat_store_dwordx4 v[154:155], v[146:149] offset:64 sc1

.LBB0_458:
	s_add_u32 s26, s8, s26
	s_addc_u32 s27, s9, s27
	s_lshl_b32 s1, s1, 3
	s_add_u32 s24, s54, s1
	s_addc_u32 s25, s55, 0
	s_sub_i32 s0, s6, s0
	s_lshl_b32 s0, s0, 8
	v_readlane_b32 s1, v255, 26
	s_or_b32 s0, s0, s1
	v_or_b32_e32 v146, s0, v189
	v_ashrrev_i32_e32 v147, 31, v146
	v_ashrrev_i32_e32 v151, 31, v150
	v_lshl_add_u64 v[148:149], v[146:147], 1, s[26:27]
	v_lshl_add_u64 v[146:147], v[150:151], 3, s[12:13]
	global_load_dwordx2 v[152:153], v[146:147], off
	v_lshlrev_b64 v[156:157], 10, v[150:151]
	v_lshl_add_u64 v[156:157], v[148:149], 0, v[156:157]
	v_cmp_eq_u32_e32 vcc, 0, v188
	s_waitcnt vmcnt(0)
	v_xor_b32_e32 v0, v152, v153
	v_ashrrev_i32_e32 v0, 31, v0
	v_ffbh_i32_e32 v154, v153
	v_add_u32_e32 v0, 32, v0
	v_add_u32_e32 v154, -1, v154
	v_min_u32_e32 v0, v154, v0
	v_lshlrev_b64 v[152:153], v0, v[152:153]
	v_min_u32_e32 v152, 1, v152
	v_or_b32_e32 v152, v153, v152
	v_cvt_f32_i32_e32 v152, v152
	v_sub_u32_e32 v0, 32, v0
	v_ldexp_f32 v0, v152, v0
	v_mul_f32_e32 v0, 0x35800000, v0
	v_fmamk_f32 v0, v0, 0x3a000000, v180
	v_cmp_gt_f32_e64 s[6:7], s73, v0
	v_mul_f32_e32 v152, 0x4b800000, v0
	s_nop 0
	v_cndmask_b32_e64 v0, v0, v152, s[6:7]
	v_rsq_f32_e32 v0, v0
	s_nop 0
	v_mul_f32_e32 v152, 0x45800000, v0
	v_cndmask_b32_e64 v0, v0, v152, s[6:7]
	s_waitcnt lgkmcnt(0)
	v_pk_fma_f32 v[152:153], v[144:145], v[0:1], v[48:49] op_sel_hi:[1,0,1]
	v_pk_fma_f32 v[154:155], v[142:143], v[0:1], v[46:47] op_sel_hi:[1,0,1]
	v_pk_fma_f32 v[144:145], v[138:139], v[0:1], v[42:43] op_sel_hi:[1,0,1]
	v_pk_fma_f32 v[138:139], v[136:137], v[0:1], v[40:41] op_sel_hi:[1,0,1]
	v_pk_fma_f32 v[136:137], v[130:131], v[0:1], v[34:35] op_sel_hi:[1,0,1]
	v_cvt_pk_bf16_f32 v130, v154, v155
	v_pk_fma_f32 v[142:143], v[140:141], v[0:1], v[44:45] op_sel_hi:[1,0,1]
	v_pk_fma_f32 v[140:141], v[134:135], v[0:1], v[38:39] op_sel_hi:[1,0,1]
	v_pk_fma_f32 v[134:135], v[132:133], v[0:1], v[36:37] op_sel_hi:[1,0,1]
	v_cvt_pk_bf16_f32 v131, v152, v153
	v_cvt_pk_bf16_f32 v132, v144, v145
	v_cvt_pk_bf16_f32 v133, v142, v143
	flat_store_dwordx4 v[156:157], v[130:133] sc1
	v_mul_f32_e32 v0, v155, v155
	v_fmac_f32_e32 v0, v154, v154
	v_cvt_pk_bf16_f32 v130, v140, v141
	v_cvt_pk_bf16_f32 v131, v138, v139
	v_cvt_pk_bf16_f32 v132, v136, v137
	v_cvt_pk_bf16_f32 v133, v134, v135
	flat_store_dwordx4 v[156:157], v[130:133] offset:256 sc1
	s_nop 1
	v_mul_f32_e32 v130, v153, v153
	v_fmac_f32_e32 v130, v152, v152
	v_add_f32_e32 v0, v0, v130
	v_mul_f32_e32 v130, v145, v145
	v_mul_f32_e32 v131, v143, v143
	v_fmac_f32_e32 v130, v144, v144
	v_fmac_f32_e32 v131, v142, v142
	v_add_f32_e32 v130, v130, v131
	v_add_f32_e32 v0, v0, v130
	v_mul_f32_e32 v130, v141, v141
	v_mul_f32_e32 v131, v139, v139
	v_fmac_f32_e32 v130, v140, v140
	v_fmac_f32_e32 v131, v138, v138
	v_add_f32_e32 v130, v130, v131
	v_mul_f32_e32 v131, v137, v137
	v_mul_f32_e32 v132, v135, v135
	v_fmac_f32_e32 v131, v136, v136
	v_fmac_f32_e32 v132, v134, v134
	v_add_f32_e32 v131, v131, v132
	v_add_f32_e32 v130, v130, v131
	v_add_f32_e32 v0, v0, v130
	ds_swizzle_b32 v130, v0 offset:swizzle(SWAP,16)
	s_waitcnt lgkmcnt(0)
	v_add_f32_e32 v0, v0, v130
	v_mov_b32_e32 v132, v0
	s_nop 1
	v_permlane32_swap_b32_e32 v0, v132
	v_lshl_add_u64 v[130:131], v[150:151], 3, s[24:25]
	s_and_saveexec_b64 s[24:25], vcc
	s_cbranch_execz .LBB0_460
	v_add_f32_e32 v0, v0, v132
	v_mul_f32_e32 v0, 0x49800000, v0
	v_trunc_f32_e32 v0, v0
	v_mul_f32_e64 v132, |v0|, s78
	v_floor_f32_e32 v132, v132
	v_fma_f32 v133, v132, s96, |v0|
	v_cvt_u32_f32_e32 v132, v132
	v_cvt_u32_f32_e32 v133, v133
	v_ashrrev_i32_e32 v0, 31, v0
	v_xor_b32_e32 v134, v132, v0
	v_xor_b32_e32 v132, v133, v0
	v_sub_co_u32_e64 v132, s[6:7], v132, v0
	s_nop 1
	v_subb_co_u32_e64 v133, s[6:7], v134, v0, s[6:7]
	global_atomic_add_x2 v[130:131], v[132:133], off
.LBB0_460:
	s_or_b64 exec, exec, s[24:25]
	global_load_dwordx2 v[134:135], v[146:147], off offset:128
	v_or_b32_e32 v132, 16, v150
	v_ashrrev_i32_e32 v133, 31, v132
	v_lshlrev_b64 v[132:133], 10, v[132:133]
	v_lshl_add_u64 v[132:133], v[148:149], 0, v[132:133]
	s_waitcnt vmcnt(0)
	v_xor_b32_e32 v136, v134, v135
	v_ffbh_i32_e32 v0, v135
	v_ashrrev_i32_e32 v136, 31, v136
	v_add_u32_e32 v0, -1, v0
	v_add_u32_e32 v136, 32, v136
	v_min_u32_e32 v0, v0, v136
	v_lshlrev_b64 v[134:135], v0, v[134:135]
	v_min_u32_e32 v134, 1, v134
	v_or_b32_e32 v134, v135, v134
	v_cvt_f32_i32_e32 v134, v134
	v_sub_u32_e32 v0, 32, v0
	v_ldexp_f32 v0, v134, v0
	v_mul_f32_e32 v0, 0x35800000, v0
	v_fmamk_f32 v0, v0, 0x3a000000, v180
	v_cmp_gt_f32_e64 s[6:7], s73, v0
	v_mul_f32_e32 v134, 0x4b800000, v0
	s_nop 0
	v_cndmask_b32_e64 v0, v0, v134, s[6:7]
	v_rsq_f32_e32 v0, v0
	s_nop 0
	v_mul_f32_e32 v134, 0x45800000, v0
	v_cndmask_b32_e64 v0, v0, v134, s[6:7]
	v_pk_fma_f32 v[126:127], v[126:127], v[0:1], v[46:47] op_sel_hi:[1,0,1]
	v_pk_fma_f32 v[136:137], v[118:119], v[0:1], v[38:39] op_sel_hi:[1,0,1]
	v_cvt_pk_bf16_f32 v118, v126, v127
	v_pk_fma_f32 v[128:129], v[128:129], v[0:1], v[48:49] op_sel_hi:[1,0,1]
	v_pk_fma_f32 v[124:125], v[124:125], v[0:1], v[44:45] op_sel_hi:[1,0,1]
	v_pk_fma_f32 v[122:123], v[122:123], v[0:1], v[42:43] op_sel_hi:[1,0,1]
	v_pk_fma_f32 v[134:135], v[120:121], v[0:1], v[40:41] op_sel_hi:[1,0,1]
	v_cvt_pk_bf16_f32 v119, v128, v129
	v_cvt_pk_bf16_f32 v120, v122, v123
	v_cvt_pk_bf16_f32 v121, v124, v125
	flat_store_dwordx4 v[132:133], v[118:121] sc1
	v_pk_fma_f32 v[116:117], v[116:117], v[0:1], v[36:37] op_sel_hi:[1,0,1]
	v_pk_fma_f32 v[114:115], v[114:115], v[0:1], v[34:35] op_sel_hi:[1,0,1]
	v_cvt_pk_bf16_f32 v118, v136, v137
	v_cvt_pk_bf16_f32 v119, v134, v135
	v_mul_f32_e32 v0, v127, v127
	v_cvt_pk_bf16_f32 v120, v114, v115
	v_cvt_pk_bf16_f32 v121, v116, v117
	flat_store_dwordx4 v[132:133], v[118:121] offset:256 sc1
	v_fmac_f32_e32 v0, v126, v126
	v_mul_f32_e32 v115, v115, v115
	v_mul_f32_e32 v118, v129, v129
	v_fmac_f32_e32 v118, v128, v128
	v_add_f32_e32 v0, v0, v118
	v_mul_f32_e32 v118, v123, v123
	v_mul_f32_e32 v119, v125, v125
	v_fmac_f32_e32 v118, v122, v122
	v_fmac_f32_e32 v119, v124, v124
	v_add_f32_e32 v118, v118, v119
	v_add_f32_e32 v0, v0, v118
	v_mul_f32_e32 v118, v137, v137
	v_mul_f32_e32 v119, v135, v135
	v_fmac_f32_e32 v115, v114, v114
	v_mul_f32_e32 v114, v117, v117
	v_fmac_f32_e32 v118, v136, v136
	v_fmac_f32_e32 v119, v134, v134
	v_fmac_f32_e32 v114, v116, v116
	v_add_f32_e32 v118, v118, v119
	v_add_f32_e32 v114, v115, v114
	v_add_f32_e32 v114, v118, v114
	v_add_f32_e32 v0, v0, v114
	ds_swizzle_b32 v114, v0 offset:swizzle(SWAP,16)
	s_waitcnt lgkmcnt(0)
	v_add_f32_e32 v0, v0, v114
	v_mov_b32_e32 v114, v0
	s_nop 1
	v_permlane32_swap_b32_e32 v0, v114
	s_and_saveexec_b64 s[24:25], vcc
	s_cbranch_execz .LBB0_462
	v_add_f32_e32 v0, v0, v114
	v_mul_f32_e32 v0, 0x49800000, v0
	v_trunc_f32_e32 v0, v0
	v_mul_f32_e64 v114, |v0|, s78
	v_floor_f32_e32 v114, v114
	v_fma_f32 v115, v114, s96, |v0|
	v_cvt_u32_f32_e32 v114, v114
	v_cvt_u32_f32_e32 v115, v115
	v_ashrrev_i32_e32 v0, 31, v0
	v_xor_b32_e32 v116, v114, v0
	v_xor_b32_e32 v114, v115, v0
	v_sub_co_u32_e64 v114, s[6:7], v114, v0
	s_nop 1
	v_subb_co_u32_e64 v115, s[6:7], v116, v0, s[6:7]
	global_atomic_add_x2 v[130:131], v[114:115], off offset:128
.LBB0_462:
	s_or_b64 exec, exec, s[24:25]
	global_load_dwordx2 v[116:117], v[146:147], off offset:256
	v_or_b32_e32 v114, 32, v150
	v_ashrrev_i32_e32 v115, 31, v114
	v_lshlrev_b64 v[114:115], 10, v[114:115]
	v_lshl_add_u64 v[114:115], v[148:149], 0, v[114:115]
	s_waitcnt vmcnt(0)
	v_xor_b32_e32 v118, v116, v117
	v_ffbh_i32_e32 v0, v117
	v_ashrrev_i32_e32 v118, 31, v118
	v_add_u32_e32 v0, -1, v0
	v_add_u32_e32 v118, 32, v118
	v_min_u32_e32 v0, v0, v118
	v_lshlrev_b64 v[116:117], v0, v[116:117]
	v_min_u32_e32 v116, 1, v116
	v_or_b32_e32 v116, v117, v116
	v_cvt_f32_i32_e32 v116, v116
	v_sub_u32_e32 v0, 32, v0
	v_ldexp_f32 v0, v116, v0
	v_mul_f32_e32 v0, 0x35800000, v0
	v_fmamk_f32 v0, v0, 0x3a000000, v180
	v_cmp_gt_f32_e64 s[6:7], s73, v0
	v_mul_f32_e32 v116, 0x4b800000, v0
	s_nop 0
	v_cndmask_b32_e64 v0, v0, v116, s[6:7]
	v_rsq_f32_e32 v0, v0
	s_nop 0
	v_mul_f32_e32 v116, 0x45800000, v0
	v_cndmask_b32_e64 v0, v0, v116, s[6:7]
	v_pk_fma_f32 v[110:111], v[110:111], v[0:1], v[46:47] op_sel_hi:[1,0,1]
	v_pk_fma_f32 v[118:119], v[102:103], v[0:1], v[38:39] op_sel_hi:[1,0,1]
	v_cvt_pk_bf16_f32 v102, v110, v111
	v_pk_fma_f32 v[112:113], v[112:113], v[0:1], v[48:49] op_sel_hi:[1,0,1]
	v_pk_fma_f32 v[108:109], v[108:109], v[0:1], v[44:45] op_sel_hi:[1,0,1]
	v_pk_fma_f32 v[106:107], v[106:107], v[0:1], v[42:43] op_sel_hi:[1,0,1]
	v_pk_fma_f32 v[116:117], v[104:105], v[0:1], v[40:41] op_sel_hi:[1,0,1]
	v_cvt_pk_bf16_f32 v103, v112, v113
	v_cvt_pk_bf16_f32 v104, v106, v107
	v_cvt_pk_bf16_f32 v105, v108, v109
	flat_store_dwordx4 v[114:115], v[102:105] sc1
	v_pk_fma_f32 v[100:101], v[100:101], v[0:1], v[36:37] op_sel_hi:[1,0,1]
	v_pk_fma_f32 v[98:99], v[98:99], v[0:1], v[34:35] op_sel_hi:[1,0,1]
	v_cvt_pk_bf16_f32 v102, v118, v119
	v_cvt_pk_bf16_f32 v103, v116, v117
	v_mul_f32_e32 v0, v111, v111
	v_cvt_pk_bf16_f32 v104, v98, v99
	v_cvt_pk_bf16_f32 v105, v100, v101
	flat_store_dwordx4 v[114:115], v[102:105] offset:256 sc1
	v_fmac_f32_e32 v0, v110, v110
	v_mul_f32_e32 v99, v99, v99
	v_mul_f32_e32 v102, v113, v113
	v_fmac_f32_e32 v102, v112, v112
	v_add_f32_e32 v0, v0, v102
	v_mul_f32_e32 v102, v107, v107
	v_mul_f32_e32 v103, v109, v109
	v_fmac_f32_e32 v102, v106, v106
	v_fmac_f32_e32 v103, v108, v108
	v_add_f32_e32 v102, v102, v103
	v_add_f32_e32 v0, v0, v102
	v_mul_f32_e32 v102, v119, v119
	v_mul_f32_e32 v103, v117, v117
	v_fmac_f32_e32 v99, v98, v98
	v_mul_f32_e32 v98, v101, v101
	v_fmac_f32_e32 v102, v118, v118
	v_fmac_f32_e32 v103, v116, v116
	v_fmac_f32_e32 v98, v100, v100
	v_add_f32_e32 v102, v102, v103
	v_add_f32_e32 v98, v99, v98
	v_add_f32_e32 v98, v102, v98
	v_add_f32_e32 v0, v0, v98
	ds_swizzle_b32 v98, v0 offset:swizzle(SWAP,16)
	s_waitcnt lgkmcnt(0)
	v_add_f32_e32 v0, v0, v98
	v_mov_b32_e32 v98, v0
	s_nop 1
	v_permlane32_swap_b32_e32 v0, v98
	s_and_saveexec_b64 s[24:25], vcc
	s_cbranch_execz .LBB0_464
	v_add_f32_e32 v0, v0, v98
	v_mul_f32_e32 v0, 0x49800000, v0
	v_trunc_f32_e32 v0, v0
	v_mul_f32_e64 v98, |v0|, s78
	v_floor_f32_e32 v98, v98
	v_fma_f32 v99, v98, s96, |v0|
	v_cvt_u32_f32_e32 v98, v98
	v_cvt_u32_f32_e32 v99, v99
	v_ashrrev_i32_e32 v0, 31, v0
	v_xor_b32_e32 v100, v98, v0
	v_xor_b32_e32 v98, v99, v0
	v_sub_co_u32_e64 v98, s[6:7], v98, v0
	s_nop 1
	v_subb_co_u32_e64 v99, s[6:7], v100, v0, s[6:7]
	global_atomic_add_x2 v[130:131], v[98:99], off offset:256
.LBB0_464:
	s_or_b64 exec, exec, s[24:25]
	global_load_dwordx2 v[100:101], v[146:147], off offset:384
	v_or_b32_e32 v98, 48, v150
	v_ashrrev_i32_e32 v99, 31, v98
	v_lshlrev_b64 v[98:99], 10, v[98:99]
	v_lshl_add_u64 v[98:99], v[148:149], 0, v[98:99]
	s_waitcnt vmcnt(0)
	v_xor_b32_e32 v102, v100, v101
	v_ffbh_i32_e32 v0, v101
	v_ashrrev_i32_e32 v102, 31, v102
	v_add_u32_e32 v0, -1, v0
	v_add_u32_e32 v102, 32, v102
	v_min_u32_e32 v0, v0, v102
	v_lshlrev_b64 v[100:101], v0, v[100:101]
	v_min_u32_e32 v100, 1, v100
	v_or_b32_e32 v100, v101, v100
	v_cvt_f32_i32_e32 v100, v100
	v_sub_u32_e32 v0, 32, v0
	v_ldexp_f32 v0, v100, v0
	v_mul_f32_e32 v0, 0x35800000, v0
	v_fmamk_f32 v0, v0, 0x3a000000, v180
	v_cmp_gt_f32_e64 s[6:7], s73, v0
	v_mul_f32_e32 v100, 0x4b800000, v0
	s_nop 0
	v_cndmask_b32_e64 v0, v0, v100, s[6:7]
	v_rsq_f32_e32 v0, v0
	s_nop 0
	v_mul_f32_e32 v100, 0x45800000, v0
	v_cndmask_b32_e64 v0, v0, v100, s[6:7]
	v_pk_fma_f32 v[94:95], v[94:95], v[0:1], v[46:47] op_sel_hi:[1,0,1]
	v_pk_fma_f32 v[102:103], v[86:87], v[0:1], v[38:39] op_sel_hi:[1,0,1]
	v_cvt_pk_bf16_f32 v86, v94, v95
	v_pk_fma_f32 v[96:97], v[96:97], v[0:1], v[48:49] op_sel_hi:[1,0,1]
	v_pk_fma_f32 v[92:93], v[92:93], v[0:1], v[44:45] op_sel_hi:[1,0,1]
	v_pk_fma_f32 v[90:91], v[90:91], v[0:1], v[42:43] op_sel_hi:[1,0,1]
	v_pk_fma_f32 v[100:101], v[88:89], v[0:1], v[40:41] op_sel_hi:[1,0,1]
	v_cvt_pk_bf16_f32 v87, v96, v97
	v_cvt_pk_bf16_f32 v88, v90, v91
	v_cvt_pk_bf16_f32 v89, v92, v93
	flat_store_dwordx4 v[98:99], v[86:89] sc1
	v_pk_fma_f32 v[84:85], v[84:85], v[0:1], v[36:37] op_sel_hi:[1,0,1]
	v_pk_fma_f32 v[82:83], v[82:83], v[0:1], v[34:35] op_sel_hi:[1,0,1]
	v_cvt_pk_bf16_f32 v86, v102, v103
	v_cvt_pk_bf16_f32 v87, v100, v101
	v_mul_f32_e32 v0, v95, v95
	v_cvt_pk_bf16_f32 v88, v82, v83
	v_cvt_pk_bf16_f32 v89, v84, v85
	flat_store_dwordx4 v[98:99], v[86:89] offset:256 sc1
	v_fmac_f32_e32 v0, v94, v94
	v_mul_f32_e32 v83, v83, v83
	v_mul_f32_e32 v86, v97, v97
	v_fmac_f32_e32 v86, v96, v96
	v_add_f32_e32 v0, v0, v86
	v_mul_f32_e32 v86, v91, v91
	v_mul_f32_e32 v87, v93, v93
	v_fmac_f32_e32 v86, v90, v90
	v_fmac_f32_e32 v87, v92, v92
	v_add_f32_e32 v86, v86, v87
	v_add_f32_e32 v0, v0, v86
	v_mul_f32_e32 v86, v103, v103
	v_mul_f32_e32 v87, v101, v101
	v_fmac_f32_e32 v83, v82, v82
	v_mul_f32_e32 v82, v85, v85
	v_fmac_f32_e32 v86, v102, v102
	v_fmac_f32_e32 v87, v100, v100
	v_fmac_f32_e32 v82, v84, v84
	v_add_f32_e32 v86, v86, v87
	v_add_f32_e32 v82, v83, v82
	v_add_f32_e32 v82, v86, v82
	v_add_f32_e32 v0, v0, v82
	ds_swizzle_b32 v82, v0 offset:swizzle(SWAP,16)
	s_waitcnt lgkmcnt(0)
	v_add_f32_e32 v0, v0, v82
	v_mov_b32_e32 v82, v0
	s_nop 1
	v_permlane32_swap_b32_e32 v0, v82
	s_and_saveexec_b64 s[24:25], vcc
	s_cbranch_execz .LBB0_466
	v_add_f32_e32 v0, v0, v82
	v_mul_f32_e32 v0, 0x49800000, v0
	v_trunc_f32_e32 v0, v0
	v_mul_f32_e64 v82, |v0|, s78
	v_floor_f32_e32 v82, v82
	v_fma_f32 v83, v82, s96, |v0|
	v_cvt_u32_f32_e32 v82, v82
	v_cvt_u32_f32_e32 v83, v83
	v_ashrrev_i32_e32 v0, 31, v0
	v_xor_b32_e32 v84, v82, v0
	v_xor_b32_e32 v82, v83, v0
	v_sub_co_u32_e64 v82, s[6:7], v82, v0
	s_nop 1
	v_subb_co_u32_e64 v83, s[6:7], v84, v0, s[6:7]
	global_atomic_add_x2 v[130:131], v[82:83], off offset:384
.LBB0_466:
	s_or_b64 exec, exec, s[24:25]
	global_load_dwordx2 v[82:83], v[146:147], off offset:1024
	v_lshlrev_b64 v[88:89], 10, v[150:151]
	s_mov_b64 s[0:1], 0x20000
	s_waitcnt vmcnt(0)
	v_xor_b32_e32 v84, v82, v83
	v_ffbh_i32_e32 v0, v83
	v_ashrrev_i32_e32 v84, 31, v84
	v_add_u32_e32 v0, -1, v0
	v_add_u32_e32 v84, 32, v84
	v_min_u32_e32 v0, v0, v84
	v_lshlrev_b64 v[82:83], v0, v[82:83]
	v_min_u32_e32 v82, 1, v82
	v_or_b32_e32 v82, v83, v82
	v_cvt_f32_i32_e32 v82, v82
	v_sub_u32_e32 v0, 32, v0
	v_ldexp_f32 v0, v82, v0
	v_mul_f32_e32 v0, 0x35800000, v0
	v_fmamk_f32 v0, v0, 0x3a000000, v180
	v_cmp_gt_f32_e64 s[6:7], s73, v0
	v_mul_f32_e32 v82, 0x4b800000, v0
	s_nop 0
	v_cndmask_b32_e64 v0, v0, v82, s[6:7]
	v_rsq_f32_e32 v0, v0
	s_nop 0
	v_mul_f32_e32 v82, 0x45800000, v0
	v_cndmask_b32_e64 v0, v0, v82, s[6:7]
	v_pk_fma_f32 v[82:83], v[78:79], v[0:1], v[46:47] op_sel_hi:[1,0,1]
	v_pk_fma_f32 v[78:79], v[74:75], v[0:1], v[42:43] op_sel_hi:[1,0,1]
	v_pk_fma_f32 v[74:75], v[70:71], v[0:1], v[38:39] op_sel_hi:[1,0,1]
	v_pk_fma_f32 v[70:71], v[66:67], v[0:1], v[34:35] op_sel_hi:[1,0,1]
	v_lshl_add_u64 v[66:67], v[148:149], 0, v[88:89]
	v_lshl_add_u64 v[88:89], v[66:67], 0, s[0:1]
	s_mov_b32 s0, 0x20000
	v_add_co_u32_e64 v90, s[6:7], s0, v66
	v_pk_fma_f32 v[80:81], v[80:81], v[0:1], v[48:49] op_sel_hi:[1,0,1]
	v_pk_fma_f32 v[76:77], v[76:77], v[0:1], v[44:45] op_sel_hi:[1,0,1]
	v_pk_fma_f32 v[72:73], v[72:73], v[0:1], v[40:41] op_sel_hi:[1,0,1]
	v_pk_fma_f32 v[68:69], v[68:69], v[0:1], v[36:37] op_sel_hi:[1,0,1]
	v_cvt_pk_bf16_f32 v84, v82, v83
	v_cvt_pk_bf16_f32 v85, v80, v81
	v_cvt_pk_bf16_f32 v86, v78, v79
	v_cvt_pk_bf16_f32 v87, v76, v77
	v_addc_co_u32_e64 v91, s[6:7], 0, v67, s[6:7]
	flat_store_dwordx4 v[90:91], v[84:87] sc1
	v_mul_f32_e32 v0, v83, v83
	v_mul_f32_e32 v81, v81, v81
	v_cvt_pk_bf16_f32 v84, v74, v75
	v_cvt_pk_bf16_f32 v85, v72, v73
	v_cvt_pk_bf16_f32 v86, v70, v71
	v_cvt_pk_bf16_f32 v87, v68, v69
	v_mul_f32_e32 v79, v79, v79
	v_mul_f32_e32 v77, v77, v77
	v_mul_f32_e32 v75, v75, v75
	v_mul_f32_e32 v73, v73, v73
	v_mul_f32_e32 v71, v71, v71
	v_mul_f32_e32 v69, v69, v69
	v_fmac_f32_e32 v0, v82, v82
	v_fmac_f32_e32 v81, v80, v80
	v_fmac_f32_e32 v79, v78, v78
	v_fmac_f32_e32 v77, v76, v76
	v_fmac_f32_e32 v75, v74, v74
	v_fmac_f32_e32 v73, v72, v72
	v_fmac_f32_e32 v71, v70, v70
	v_fmac_f32_e32 v69, v68, v68
	v_add_f32_e32 v0, v0, v81
	v_add_f32_e32 v76, v79, v77
	v_add_f32_e32 v72, v75, v73
	v_add_f32_e32 v68, v71, v69
	v_add_f32_e32 v0, v0, v76
	v_add_f32_e32 v68, v72, v68
	v_add_f32_e32 v0, v0, v68
	ds_swizzle_b32 v68, v0 offset:swizzle(SWAP,16)
	flat_store_dwordx4 v[88:89], v[84:87] offset:256 sc1
	s_waitcnt lgkmcnt(0)
	v_add_f32_e32 v0, v0, v68
	v_mov_b32_e32 v68, v0
	s_nop 1
	v_permlane32_swap_b32_e32 v0, v68
	s_and_saveexec_b64 s[24:25], vcc
	s_cbranch_execz .LBB0_468
	v_add_f32_e32 v0, v0, v68
	v_mul_f32_e32 v0, 0x49800000, v0
	v_trunc_f32_e32 v0, v0
	v_mul_f32_e64 v68, |v0|, s78
	v_floor_f32_e32 v68, v68
	v_fma_f32 v69, v68, s96, |v0|
	v_cvt_u32_f32_e32 v68, v68
	v_cvt_u32_f32_e32 v69, v69
	v_ashrrev_i32_e32 v0, 31, v0
	v_xor_b32_e32 v70, v68, v0
	v_xor_b32_e32 v68, v69, v0
	v_sub_co_u32_e64 v68, s[6:7], v68, v0
	s_nop 1
	v_subb_co_u32_e64 v69, s[6:7], v70, v0, s[6:7]
	global_atomic_add_x2 v[130:131], v[68:69], off offset:1024
.LBB0_468:
	s_or_b64 exec, exec, s[24:25]
	global_load_dwordx2 v[68:69], v[146:147], off offset:1152
	s_mov_b64 s[0:1], 0x24000
	v_lshl_add_u64 v[72:73], v[66:67], 0, s[0:1]
	s_mov_b32 s0, 0x24000
	s_waitcnt vmcnt(0)
	v_xor_b32_e32 v70, v68, v69
	v_ffbh_i32_e32 v0, v69
	v_ashrrev_i32_e32 v70, 31, v70
	v_add_u32_e32 v0, -1, v0
	v_add_u32_e32 v70, 32, v70
	v_min_u32_e32 v0, v0, v70
	v_lshlrev_b64 v[68:69], v0, v[68:69]
	v_min_u32_e32 v68, 1, v68
	v_or_b32_e32 v68, v69, v68
	v_cvt_f32_i32_e32 v68, v68
	v_sub_u32_e32 v0, 32, v0
	v_ldexp_f32 v0, v68, v0
	v_mul_f32_e32 v0, 0x35800000, v0
	v_fmamk_f32 v0, v0, 0x3a000000, v180
	v_cmp_gt_f32_e64 s[6:7], s73, v0
	v_mul_f32_e32 v68, 0x4b800000, v0
	s_nop 0
	v_cndmask_b32_e64 v0, v0, v68, s[6:7]
	v_rsq_f32_e32 v0, v0
	s_nop 0
	v_mul_f32_e32 v68, 0x45800000, v0
	v_cndmask_b32_e64 v0, v0, v68, s[6:7]
	v_add_co_u32_e64 v66, s[6:7], s0, v66
	v_pk_fma_f32 v[62:63], v[62:63], v[0:1], v[46:47] op_sel_hi:[1,0,1]
	v_pk_fma_f32 v[58:59], v[58:59], v[0:1], v[42:43] op_sel_hi:[1,0,1]
	v_pk_fma_f32 v[54:55], v[54:55], v[0:1], v[38:39] op_sel_hi:[1,0,1]
	v_pk_fma_f32 v[50:51], v[50:51], v[0:1], v[34:35] op_sel_hi:[1,0,1]
	v_cvt_pk_bf16_f32 v68, v62, v63
	v_addc_co_u32_e64 v67, s[6:7], 0, v67, s[6:7]
	v_pk_fma_f32 v[64:65], v[64:65], v[0:1], v[48:49] op_sel_hi:[1,0,1]
	v_pk_fma_f32 v[60:61], v[60:61], v[0:1], v[44:45] op_sel_hi:[1,0,1]
	v_pk_fma_f32 v[56:57], v[56:57], v[0:1], v[40:41] op_sel_hi:[1,0,1]
	v_pk_fma_f32 v[52:53], v[52:53], v[0:1], v[36:37] op_sel_hi:[1,0,1]
	v_cvt_pk_bf16_f32 v69, v64, v65
	v_cvt_pk_bf16_f32 v70, v58, v59
	v_cvt_pk_bf16_f32 v71, v60, v61
	flat_store_dwordx4 v[66:67], v[68:71] sc1
	v_cvt_pk_bf16_f32 v66, v54, v55
	v_cvt_pk_bf16_f32 v67, v56, v57
	v_mul_f32_e32 v0, v63, v63
	v_mul_f32_e32 v59, v59, v59
	v_cvt_pk_bf16_f32 v68, v50, v51
	v_mul_f32_e32 v55, v55, v55
	v_mul_f32_e32 v51, v51, v51
	v_fmac_f32_e32 v0, v62, v62
	v_mul_f32_e32 v62, v65, v65
	v_fmac_f32_e32 v59, v58, v58
	v_mul_f32_e32 v58, v61, v61
	v_fmac_f32_e32 v55, v54, v54
	v_mul_f32_e32 v54, v57, v57
	v_fmac_f32_e32 v51, v50, v50
	v_mul_f32_e32 v50, v53, v53
	v_fmac_f32_e32 v62, v64, v64
	v_fmac_f32_e32 v58, v60, v60
	v_fmac_f32_e32 v54, v56, v56
	v_fmac_f32_e32 v50, v52, v52
	v_add_f32_e32 v0, v0, v62
	v_add_f32_e32 v58, v59, v58
	v_add_f32_e32 v54, v55, v54
	v_add_f32_e32 v50, v51, v50
	v_add_f32_e32 v0, v0, v58
	v_add_f32_e32 v50, v54, v50
	v_add_f32_e32 v0, v0, v50
	ds_swizzle_b32 v50, v0 offset:swizzle(SWAP,16)
	v_cvt_pk_bf16_f32 v69, v52, v53
	flat_store_dwordx4 v[72:73], v[66:69] offset:256 sc1
	s_waitcnt lgkmcnt(0)
	v_add_f32_e32 v0, v0, v50
	v_mov_b32_e32 v50, v0
	s_nop 1
	v_permlane32_swap_b32_e32 v0, v50
	s_and_saveexec_b64 s[24:25], vcc
	s_cbranch_execz .LBB0_470
	v_add_f32_e32 v0, v0, v50
	v_mul_f32_e32 v0, 0x49800000, v0
	v_trunc_f32_e32 v0, v0
	v_mul_f32_e64 v50, |v0|, s78
	v_floor_f32_e32 v50, v50
	v_fma_f32 v51, v50, s96, |v0|
	v_cvt_u32_f32_e32 v50, v50
	v_cvt_u32_f32_e32 v51, v51
	v_ashrrev_i32_e32 v0, 31, v0
	v_xor_b32_e32 v52, v50, v0
	v_xor_b32_e32 v50, v51, v0
	v_sub_co_u32_e64 v50, s[6:7], v50, v0
	s_nop 1
	v_subb_co_u32_e64 v51, s[6:7], v52, v0, s[6:7]
	global_atomic_add_x2 v[130:131], v[50:51], off offset:1152
.LBB0_470:
	s_or_b64 exec, exec, s[24:25]
	global_load_dwordx2 v[50:51], v[146:147], off offset:1280
	v_lshlrev_b64 v[56:57], 10, v[150:151]
	s_mov_b64 s[0:1], 0x28000
	s_waitcnt vmcnt(0)
	v_xor_b32_e32 v52, v50, v51
	v_ffbh_i32_e32 v0, v51
	v_ashrrev_i32_e32 v52, 31, v52
	v_add_u32_e32 v0, -1, v0
	v_add_u32_e32 v52, 32, v52
	v_min_u32_e32 v0, v0, v52
	v_lshlrev_b64 v[50:51], v0, v[50:51]
	v_min_u32_e32 v50, 1, v50
	v_or_b32_e32 v50, v51, v50
	v_cvt_f32_i32_e32 v50, v50
	v_sub_u32_e32 v0, 32, v0
	v_ldexp_f32 v0, v50, v0
	v_mul_f32_e32 v0, 0x35800000, v0
	v_fmamk_f32 v0, v0, 0x3a000000, v180
	v_cmp_gt_f32_e64 s[6:7], s73, v0
	v_mul_f32_e32 v50, 0x4b800000, v0
	s_nop 0
	v_cndmask_b32_e64 v0, v0, v50, s[6:7]
	v_rsq_f32_e32 v0, v0
	s_nop 0
	v_mul_f32_e32 v50, 0x45800000, v0
	v_cndmask_b32_e64 v0, v0, v50, s[6:7]
	v_pk_fma_f32 v[50:51], v[30:31], v[0:1], v[46:47] op_sel_hi:[1,0,1]
	v_pk_fma_f32 v[30:31], v[26:27], v[0:1], v[42:43] op_sel_hi:[1,0,1]
	v_pk_fma_f32 v[26:27], v[22:23], v[0:1], v[38:39] op_sel_hi:[1,0,1]
	v_pk_fma_f32 v[22:23], v[18:19], v[0:1], v[34:35] op_sel_hi:[1,0,1]
	v_lshl_add_u64 v[18:19], v[148:149], 0, v[56:57]
	v_lshl_add_u64 v[56:57], v[18:19], 0, s[0:1]
	s_mov_b32 s0, 0x28000
	v_add_co_u32_e64 v58, s[6:7], s0, v18
	v_pk_fma_f32 v[32:33], v[32:33], v[0:1], v[48:49] op_sel_hi:[1,0,1]
	v_pk_fma_f32 v[28:29], v[28:29], v[0:1], v[44:45] op_sel_hi:[1,0,1]
	v_pk_fma_f32 v[24:25], v[24:25], v[0:1], v[40:41] op_sel_hi:[1,0,1]
	v_pk_fma_f32 v[20:21], v[20:21], v[0:1], v[36:37] op_sel_hi:[1,0,1]
	v_cvt_pk_bf16_f32 v52, v50, v51
	v_cvt_pk_bf16_f32 v53, v32, v33
	v_cvt_pk_bf16_f32 v54, v30, v31
	v_cvt_pk_bf16_f32 v55, v28, v29
	v_addc_co_u32_e64 v59, s[6:7], 0, v19, s[6:7]
	flat_store_dwordx4 v[58:59], v[52:55] sc1
	v_mul_f32_e32 v0, v51, v51
	v_mul_f32_e32 v33, v33, v33
	v_cvt_pk_bf16_f32 v52, v26, v27
	v_cvt_pk_bf16_f32 v53, v24, v25
	v_cvt_pk_bf16_f32 v54, v22, v23
	v_cvt_pk_bf16_f32 v55, v20, v21
	v_mul_f32_e32 v31, v31, v31
	v_mul_f32_e32 v29, v29, v29
	v_mul_f32_e32 v27, v27, v27
	v_mul_f32_e32 v25, v25, v25
	v_mul_f32_e32 v23, v23, v23
	v_mul_f32_e32 v21, v21, v21
	v_fmac_f32_e32 v0, v50, v50
	v_fmac_f32_e32 v33, v32, v32
	v_fmac_f32_e32 v31, v30, v30
	v_fmac_f32_e32 v29, v28, v28
	v_fmac_f32_e32 v27, v26, v26
	v_fmac_f32_e32 v25, v24, v24
	v_fmac_f32_e32 v23, v22, v22
	v_fmac_f32_e32 v21, v20, v20
	v_add_f32_e32 v0, v0, v33
	v_add_f32_e32 v28, v31, v29
	v_add_f32_e32 v24, v27, v25
	v_add_f32_e32 v20, v23, v21
	v_add_f32_e32 v0, v0, v28
	v_add_f32_e32 v20, v24, v20
	v_add_f32_e32 v0, v0, v20
	ds_swizzle_b32 v20, v0 offset:swizzle(SWAP,16)
	flat_store_dwordx4 v[56:57], v[52:55] offset:256 sc1
	s_waitcnt lgkmcnt(0)
	v_add_f32_e32 v0, v0, v20
	v_mov_b32_e32 v20, v0
	s_nop 1
	v_permlane32_swap_b32_e32 v0, v20
	s_and_saveexec_b64 s[24:25], vcc
	s_cbranch_execz .LBB0_472
	v_add_f32_e32 v0, v0, v20
	v_mul_f32_e32 v0, 0x49800000, v0
	v_trunc_f32_e32 v0, v0
	v_mul_f32_e64 v20, |v0|, s78
	v_floor_f32_e32 v20, v20
	v_fma_f32 v21, v20, s96, |v0|
	v_cvt_u32_f32_e32 v20, v20
	v_cvt_u32_f32_e32 v21, v21
	v_ashrrev_i32_e32 v0, 31, v0
	v_xor_b32_e32 v22, v20, v0
	v_xor_b32_e32 v20, v21, v0
	v_sub_co_u32_e64 v20, s[6:7], v20, v0
	s_nop 1
	v_subb_co_u32_e64 v21, s[6:7], v22, v0, s[6:7]
	global_atomic_add_x2 v[130:131], v[20:21], off offset:1280
.LBB0_472:
	s_or_b64 exec, exec, s[24:25]
	global_load_dwordx2 v[20:21], v[146:147], off offset:1408
	s_mov_b64 s[0:1], 0x2c000
	v_lshl_add_u64 v[24:25], v[18:19], 0, s[0:1]
	s_mov_b32 s0, 0x2c000
	s_waitcnt vmcnt(0)
	v_xor_b32_e32 v22, v20, v21
	v_ffbh_i32_e32 v0, v21
	v_ashrrev_i32_e32 v22, 31, v22
	v_add_u32_e32 v0, -1, v0
	v_add_u32_e32 v22, 32, v22
	v_min_u32_e32 v0, v0, v22
	v_lshlrev_b64 v[20:21], v0, v[20:21]
	v_min_u32_e32 v20, 1, v20
	v_or_b32_e32 v20, v21, v20
	v_cvt_f32_i32_e32 v20, v20
	v_sub_u32_e32 v0, 32, v0
	v_ldexp_f32 v0, v20, v0
	v_mul_f32_e32 v0, 0x35800000, v0
	v_fmamk_f32 v0, v0, 0x3a000000, v180
	v_cmp_gt_f32_e64 s[6:7], s73, v0
	v_mul_f32_e32 v20, 0x4b800000, v0
	s_nop 0
	v_cndmask_b32_e64 v0, v0, v20, s[6:7]
	v_rsq_f32_e32 v0, v0
	s_nop 0
	v_mul_f32_e32 v20, 0x45800000, v0
	v_cndmask_b32_e64 v0, v0, v20, s[6:7]
	v_add_co_u32_e64 v18, s[6:7], s0, v18
	v_pk_fma_f32 v[14:15], v[14:15], v[0:1], v[46:47] op_sel_hi:[1,0,1]
	v_pk_fma_f32 v[10:11], v[10:11], v[0:1], v[42:43] op_sel_hi:[1,0,1]
	v_pk_fma_f32 v[6:7], v[6:7], v[0:1], v[38:39] op_sel_hi:[1,0,1]
	v_pk_fma_f32 v[2:3], v[2:3], v[0:1], v[34:35] op_sel_hi:[1,0,1]
	v_cvt_pk_bf16_f32 v20, v14, v15
	v_addc_co_u32_e64 v19, s[6:7], 0, v19, s[6:7]
	v_pk_fma_f32 v[16:17], v[16:17], v[0:1], v[48:49] op_sel_hi:[1,0,1]
	v_pk_fma_f32 v[12:13], v[12:13], v[0:1], v[44:45] op_sel_hi:[1,0,1]
	v_pk_fma_f32 v[8:9], v[8:9], v[0:1], v[40:41] op_sel_hi:[1,0,1]
	v_pk_fma_f32 v[4:5], v[4:5], v[0:1], v[36:37] op_sel_hi:[1,0,1]
	v_cvt_pk_bf16_f32 v21, v16, v17
	v_cvt_pk_bf16_f32 v22, v10, v11
	v_cvt_pk_bf16_f32 v23, v12, v13
	flat_store_dwordx4 v[18:19], v[20:23] sc1
	v_cvt_pk_bf16_f32 v18, v6, v7
	v_cvt_pk_bf16_f32 v19, v8, v9
	v_mul_f32_e32 v0, v15, v15
	v_mul_f32_e32 v11, v11, v11
	v_cvt_pk_bf16_f32 v20, v2, v3
	v_mul_f32_e32 v7, v7, v7
	v_mul_f32_e32 v3, v3, v3
	v_fmac_f32_e32 v0, v14, v14
	v_mul_f32_e32 v14, v17, v17
	v_fmac_f32_e32 v11, v10, v10
	v_mul_f32_e32 v10, v13, v13
	v_fmac_f32_e32 v7, v6, v6
	v_mul_f32_e32 v6, v9, v9
	v_fmac_f32_e32 v3, v2, v2
	v_mul_f32_e32 v2, v5, v5
	v_fmac_f32_e32 v14, v16, v16
	v_fmac_f32_e32 v10, v12, v12
	v_fmac_f32_e32 v6, v8, v8
	v_fmac_f32_e32 v2, v4, v4
	v_add_f32_e32 v0, v0, v14
	v_add_f32_e32 v10, v11, v10
	v_add_f32_e32 v6, v7, v6
	v_add_f32_e32 v2, v3, v2
	v_add_f32_e32 v0, v0, v10
	v_add_f32_e32 v2, v6, v2
	v_add_f32_e32 v0, v0, v2
	ds_swizzle_b32 v2, v0 offset:swizzle(SWAP,16)
	v_cvt_pk_bf16_f32 v21, v4, v5
	flat_store_dwordx4 v[24:25], v[18:21] offset:256 sc1
	s_waitcnt lgkmcnt(0)
	v_add_f32_e32 v0, v0, v2
	v_mov_b32_e32 v2, v0
	s_nop 1
	v_permlane32_swap_b32_e32 v0, v2
	s_and_saveexec_b64 s[6:7], vcc
	s_cbranch_execz .LBB0_474
	v_add_f32_e32 v0, v0, v2
	v_mul_f32_e32 v0, 0x49800000, v0
	v_trunc_f32_e32 v0, v0
	v_mul_f32_e64 v2, |v0|, s78
	v_floor_f32_e32 v2, v2
	v_fma_f32 v3, v2, s96, |v0|
	v_cvt_u32_f32_e32 v2, v2
	v_cvt_u32_f32_e32 v3, v3
	v_ashrrev_i32_e32 v0, 31, v0
	v_xor_b32_e32 v4, v2, v0
	v_xor_b32_e32 v2, v3, v0
	v_sub_co_u32_e32 v2, vcc, v2, v0
	s_nop 1
	v_subb_co_u32_e32 v3, vcc, v4, v0, vcc
	global_atomic_add_x2 v[130:131], v[2:3], off offset:1408
